# attention phases: one static s_setprio 1 for waves 4-7 at phase entry, per-MFMA-group setprio pairs removed
# speedup vs baseline: 1.0018x; 1.0018x over previous
.LBB0_378:
	s_cmp_lt_i32 s82, 4
	s_cselect_b64 s[0:1], -1, 0
	s_waitcnt lgkmcnt(0)
	s_and_b64 s[44:45], s[0:1], s[2:3]
	s_andn2_b64 vcc, exec, s[44:45]
	s_cbranch_vccnz .LBB0_509
	s_and_b32 s0, s33, 1
	s_cmp_eq_u32 s0, 0
	s_cselect_b64 s[48:49], -1, 0
	s_cmp_eq_u32 s0, 1
	s_cselect_b64 s[0:1], -1, 0
	s_movk_i32 s52, 0x100
	s_movk_i32 s50, 0x80
	s_mov_b32 s74, 0
	s_and_b64 vcc, exec, s[0:1]
	s_cbranch_vccz .LBB0_386
	s_mul_i32 s4, s92, 0x1d1
	v_lshrrev_b32_e32 v0, 5, v180
	v_and_b32_e32 v7, 31, v180
	v_mul_u32_u24_e32 v0, 31, v0
	v_add3_u32 v0, s4, v0, v7
	v_lshlrev_b32_e32 v0, 2, v0
	v_cmp_ne_u32_e32 vcc, 31, v7
	v_lshlrev_b32_e32 v16, 2, v180
	v_mov_b32_e32 v20, 0
	v_mov_b32_e32 v21, 0
	v_mov_b32_e32 v22, 0
	v_mov_b32_e32 v23, 0
	v_mov_b32_e32 v24, 0
	v_mov_b32_e32 v25, 0
	v_mov_b32_e32 v26, 0
	v_mov_b32_e32 v27, 0
	s_waitcnt lgkmcnt(0)
	global_load_dword v2, v16, s[40:41]
	global_load_dword v3, v16, s[42:43]
	s_mov_b64 s[2:3], exec
	v_cmp_gt_u32_e64 s[0:1], 32, v180
	s_and_b64 exec, exec, vcc
	global_load_dword v20, v0, s[46:47]
	global_load_dword v21, v0, s[46:47] offset:248
	global_load_dword v22, v0, s[46:47] offset:496
	global_load_dword v23, v0, s[46:47] offset:744
	global_load_dword v24, v0, s[46:47] offset:992
	global_load_dword v25, v0, s[46:47] offset:1240
	global_load_dword v26, v0, s[46:47] offset:1488
	s_and_b64 exec, exec, s[0:1]
	global_load_dword v27, v0, s[46:47] offset:1736
	s_mov_b64 exec, s[2:3]
	v_xor_b32_e32 v8, 1, v180
	v_lshlrev_b32_e32 v8, 2, v8
	v_xor_b32_e32 v9, 2, v180
	v_lshlrev_b32_e32 v9, 2, v9
	v_xor_b32_e32 v10, 4, v180
	v_lshlrev_b32_e32 v10, 2, v10
	v_xor_b32_e32 v11, 8, v180
	v_lshlrev_b32_e32 v11, 2, v11
	v_xor_b32_e32 v137, 16, v180
	v_lshlrev_b32_e32 v137, 2, v137
	v_xor_b32_e32 v138, 32, v180
	v_lshlrev_b32_e32 v138, 2, v138
	s_mul_i32 s5, s92, 0x780
	v_add_u32_e32 v16, s5, v16
	v_add_u32_e32 v16, 0xa000, v16
	s_waitcnt vmcnt(8)
	v_max_f32_e64 v5, |v2|, |v2|
	v_max_f32_e64 v6, |v3|, |v3|
	s_waitcnt vmcnt(0)
	v_max_f32_e64 v1, |v20|, |v21|
	v_max_f32_e64 v4, |v22|, |v23|
	v_max_f32_e64 v12, |v24|, |v25|
	v_max_f32_e64 v13, |v26|, |v27|
	v_max_f32_e32 v1, v1, v4
	v_max_f32_e32 v12, v12, v13
	v_max_f32_e32 v1, v1, v12
	ds_bpermute_b32 v12, v8, v1
	ds_bpermute_b32 v13, v8, v5
	ds_bpermute_b32 v14, v8, v6
	s_waitcnt lgkmcnt(0)
	v_max_f32_e32 v1, v1, v12
	v_max_f32_e32 v5, v5, v13
	v_max_f32_e32 v6, v6, v14
	ds_bpermute_b32 v12, v9, v1
	ds_bpermute_b32 v13, v9, v5
	ds_bpermute_b32 v14, v9, v6
	s_waitcnt lgkmcnt(0)
	v_max_f32_e32 v1, v1, v12
	v_max_f32_e32 v5, v5, v13
	v_max_f32_e32 v6, v6, v14
	ds_bpermute_b32 v12, v10, v1
	ds_bpermute_b32 v13, v10, v5
	ds_bpermute_b32 v14, v10, v6
	s_waitcnt lgkmcnt(0)
	v_max_f32_e32 v1, v1, v12
	v_max_f32_e32 v5, v5, v13
	v_max_f32_e32 v6, v6, v14
	ds_bpermute_b32 v12, v11, v1
	ds_bpermute_b32 v13, v11, v5
	ds_bpermute_b32 v14, v11, v6
	s_waitcnt lgkmcnt(0)
	v_max_f32_e32 v1, v1, v12
	v_max_f32_e32 v5, v5, v13
	v_max_f32_e32 v6, v6, v14
	ds_bpermute_b32 v12, v137, v1
	ds_bpermute_b32 v13, v137, v5
	ds_bpermute_b32 v14, v137, v6
	s_waitcnt lgkmcnt(0)
	v_max_f32_e32 v1, v1, v12
	v_max_f32_e32 v5, v5, v13
	v_max_f32_e32 v6, v6, v14
	ds_bpermute_b32 v12, v138, v1
	ds_bpermute_b32 v13, v138, v5
	ds_bpermute_b32 v14, v138, v6
	s_waitcnt lgkmcnt(0)
	v_max_f32_e32 v1, v1, v12
	v_max_f32_e32 v5, v5, v13
	v_max_f32_e32 v6, v6, v14
	v_mul_f32_e32 v5, 0x41000000, v5
	v_fmac_f32_e32 v1, v6, v5
	v_mov_b32_e32 v15, 0xf149f2ca
	v_sub_f32_e32 v12, v20, v1
	v_mul_f32_e32 v12, 0x3fb8aa3b, v12
	v_cndmask_b32_e32 v12, v15, v12, vcc
	ds_write_b32 v16, v12
	v_sub_f32_e32 v12, v21, v1
	v_mul_f32_e32 v12, 0x3fb8aa3b, v12
	v_cndmask_b32_e32 v12, v15, v12, vcc
	ds_write_b32 v16, v12 offset:256
	v_sub_f32_e32 v12, v22, v1
	v_mul_f32_e32 v12, 0x3fb8aa3b, v12
	v_cndmask_b32_e32 v12, v15, v12, vcc
	ds_write_b32 v16, v12 offset:512
	v_sub_f32_e32 v12, v23, v1
	v_mul_f32_e32 v12, 0x3fb8aa3b, v12
	v_cndmask_b32_e32 v12, v15, v12, vcc
	ds_write_b32 v16, v12 offset:768
	v_sub_f32_e32 v12, v24, v1
	v_mul_f32_e32 v12, 0x3fb8aa3b, v12
	v_cndmask_b32_e32 v12, v15, v12, vcc
	ds_write_b32 v16, v12 offset:1024
	v_sub_f32_e32 v12, v25, v1
	v_mul_f32_e32 v12, 0x3fb8aa3b, v12
	v_cndmask_b32_e32 v12, v15, v12, vcc
	ds_write_b32 v16, v12 offset:1280
	v_sub_f32_e32 v12, v26, v1
	v_mul_f32_e32 v12, 0x3fb8aa3b, v12
	v_cndmask_b32_e32 v12, v15, v12, vcc
	ds_write_b32 v16, v12 offset:1536
	v_sub_f32_e32 v12, v27, v1
	v_mul_f32_e32 v12, 0x3fb8aa3b, v12
	v_cndmask_b32_e32 v12, v15, v12, vcc
	s_and_b64 exec, exec, s[0:1]
	ds_write_b32 v16, v12 offset:1792
	s_mov_b64 exec, s[2:3]
	s_cmp_ge_u32 s92, 4
	s_cbranch_scc0 .Lprio_a0
	s_setprio 1
.Lprio_a0:
	s_mov_b64 s[2:3], -1
	s_branch .LBB0_387

.LBB0_405:
	s_add_i32 s72, s60, -3
	s_cmp_ge_u32 s72, s38
	s_cselect_b64 s[68:69], -1, 0
	s_cmp_lt_u32 s72, s39
	s_cselect_b64 vcc, -1, 0
	s_and_b64 s[68:69], s[68:69], vcc
	s_andn2_b64 vcc, exec, s[68:69]
	s_cbranch_vccnz .LBB0_407
	v_add_u32_e32 v178, v150, v149
	v_add_u32_e32 v181, 0x2000, v178
	v_add_u32_e32 v218, 0x2800, v178
	v_add_u32_e32 v219, 0x3000, v178
	v_add_u32_e32 v178, v150, v151
	v_add_u32_e32 v119, v148, v149
	v_add_u32_e32 v136, s70, v152
	v_add_u32_sdwa v163, s70, v143 dst_sel:DWORD dst_unused:UNUSED_PAD src0_sel:DWORD src1_sel:BYTE_2
	v_add_u32_sdwa v165, s70, v143 dst_sel:DWORD dst_unused:UNUSED_PAD src0_sel:DWORD src1_sel:BYTE_3
	v_add_u32_e32 v220, 0x2000, v178
	v_add_u32_sdwa v179, s70, v141 dst_sel:DWORD dst_unused:UNUSED_PAD src0_sel:DWORD src1_sel:BYTE_1
	ds_read_b128 v[158:161], v119
	ds_read_b128 v[166:169], v119 offset:64
	ds_read_b128 v[170:173], v119 offset:2304
	ds_read_b128 v[174:177], v119 offset:2368
	v_add_u32_e32 v162, s70, v153
	ds_read2_b64 v[182:185], v181 offset0:128 offset1:132
	ds_read2_b64 v[186:189], v218 offset0:160 offset1:164
	ds_read2_b64 v[190:193], v219 offset0:192 offset1:196
	ds_read2_b64 v[194:197], v220 offset0:128 offset1:132
	ds_read_b128 v[198:201], v119 offset:1152
	ds_read_b128 v[202:205], v119 offset:1216
	ds_read_b128 v[206:209], v119 offset:3456
	ds_read_b128 v[210:213], v119 offset:3520
	v_add_u32_e32 v178, s70, v155
	v_add_u32_sdwa v214, s70, v142 dst_sel:DWORD dst_unused:UNUSED_PAD src0_sel:DWORD src1_sel:BYTE_2
	v_add_u32_sdwa v215, s70, v142 dst_sel:DWORD dst_unused:UNUSED_PAD src0_sel:DWORD src1_sel:BYTE_3
	ds_read_b32 v136, v136 offset:41856
	ds_read_b32 v216, v162 offset:41856
	ds_read_b32 v163, v163 offset:41856
	ds_read_b32 v165, v165 offset:41856
	ds_read_b32 v217, v178 offset:41856
	ds_read_b32 v179, v179 offset:41856
	ds_read_b32 v221, v214 offset:41856
	ds_read_b32 v222, v215 offset:41856
	s_nop 0
	s_waitcnt vmcnt(7) lgkmcnt(14)
	v_mfma_f32_16x16x32_bf16 v[158:161], v[158:161], v[80:83], 0
	s_waitcnt vmcnt(6)
	v_mfma_f32_16x16x32_bf16 v[158:161], v[166:169], v[84:87], v[158:161]
	v_mfma_f32_16x16x32_bf16 v[166:169], v[170:173], v[80:83], 0
	v_mfma_f32_16x16x32_bf16 v[166:169], v[174:177], v[84:87], v[166:169]
	s_nop 0
	s_nop 6
	v_cndmask_b32_e64 v158, v166, v158, s[20:21]
	s_waitcnt lgkmcnt(7)
	v_add_f32_e32 v136, v136, v158
	v_exp_f32_e32 v162, v136
	v_cndmask_b32_e64 v136, v159, v167, s[10:11]
	v_cndmask_b32_e64 v159, v160, v168, s[12:13]
	s_waitcnt lgkmcnt(5)
	v_add_f32_e32 v159, v163, v159
	v_add_f32_e32 v136, v216, v136
	v_exp_f32_e32 v214, v159
	v_cndmask_b32_e64 v159, v161, v169, s[14:15]
	v_exp_f32_e32 v178, v136
	s_waitcnt lgkmcnt(4)
	v_add_f32_e32 v159, v165, v159
	v_exp_f32_e32 v216, v159
	v_cndmask_b32_e64 v159, v214, 0, s[12:13]
	v_cndmask_b32_e64 v158, v178, 0, s[10:11]
	v_cndmask_b32_e64 v160, 0, v178, s[10:11]
	v_cndmask_b32_e64 v161, 0, v214, s[12:13]
	v_cndmask_b32_e64 v136, 0, v162, s[20:21]
	v_cndmask_b32_e64 v166, v162, 0, s[20:21]
	v_cndmask_b32_e64 v163, v216, 0, s[14:15]
	v_cndmask_b32_e64 v165, 0, v216, s[14:15]
	v_cvt_pk_bf16_f32 v158, v136, v158
	v_cvt_pk_bf16_f32 v159, v159, v163
	v_cvt_pk_bf16_f32 v160, v166, v160
	v_cvt_pk_bf16_f32 v161, v161, v165
	s_nop 0
	v_mfma_f32_16x16x32_bf16 v[60:63], v[182:185], v[158:161], v[60:63]
	v_mfma_f32_16x16x32_bf16 v[56:59], v[186:189], v[158:161], v[56:59]
	v_mfma_f32_16x16x32_bf16 v[52:55], v[190:193], v[158:161], v[52:55]
	v_mfma_f32_16x16x32_bf16 v[48:51], v[194:197], v[158:161], v[48:51]
	s_nop 0
	ds_read2_b64 v[158:161], v181 offset0:130 offset1:134
	ds_read2_b64 v[166:169], v218 offset0:162 offset1:166
	ds_read2_b64 v[170:173], v219 offset0:194 offset1:198
	ds_read2_b64 v[174:177], v220 offset0:130 offset1:134
	ds_read_b128 v[182:185], v119 offset:3456
	ds_read_b128 v[186:189], v119 offset:3520
	ds_read_b128 v[190:193], v119 offset:5760
	ds_read_b128 v[194:197], v119 offset:5824
	v_add_u32_e32 v136, s70, v156
	v_add_u32_sdwa v165, s70, v140 dst_sel:DWORD dst_unused:UNUSED_PAD src0_sel:DWORD src1_sel:BYTE_2
	v_add_u32_sdwa v163, s70, v139 dst_sel:DWORD dst_unused:UNUSED_PAD src0_sel:DWORD src1_sel:BYTE_1
	v_add_u32_sdwa v215, s70, v140 dst_sel:DWORD dst_unused:UNUSED_PAD src0_sel:DWORD src1_sel:BYTE_3
	ds_read_b32 v136, v136 offset:41856
	ds_read_b32 v223, v163 offset:41856
	ds_read_b32 v165, v165 offset:41856
	ds_read_b32 v224, v215 offset:41856
	s_nop 0
	s_waitcnt vmcnt(5)
	v_mfma_f32_16x16x32_bf16 v[198:201], v[198:201], v[88:91], 0
	s_waitcnt vmcnt(4)
	v_mfma_f32_16x16x32_bf16 v[198:201], v[202:205], v[92:95], v[198:201]
	v_mfma_f32_16x16x32_bf16 v[202:205], v[206:209], v[88:91], 0
	v_mfma_f32_16x16x32_bf16 v[202:205], v[210:213], v[92:95], v[202:205]
	s_nop 0
	s_nop 6
	v_cndmask_b32_e64 v163, v198, v202, s[16:17]
	s_waitcnt lgkmcnt(14)
	v_add_f32_e32 v163, v217, v163
	v_cndmask_b32_e64 v198, v199, v203, s[18:19]
	v_cndmask_b32_e64 v200, v200, v204, s[6:7]
	v_exp_f32_e32 v163, v163
	v_add_f32_e32 v179, v179, v198
	s_waitcnt lgkmcnt(13)
	v_add_f32_e32 v200, v221, v200
	v_exp_f32_e32 v179, v179
	v_exp_f32_e32 v215, v200
	v_cndmask_b32_e64 v200, v201, v205, s[8:9]
	s_waitcnt lgkmcnt(12)
	v_add_f32_e32 v200, v222, v200
	v_exp_f32_e32 v217, v200
	v_cndmask_b32_e64 v198, v163, 0, s[16:17]
	v_cndmask_b32_e64 v202, 0, v163, s[16:17]
	v_pk_add_f32 v[162:163], v[162:163], 0 op_sel_hi:[1,0]
	v_cndmask_b32_e64 v199, v179, 0, s[18:19]
	v_pk_add_f32 v[162:163], v[178:179], v[162:163]
	v_cndmask_b32_e64 v200, 0, v179, s[18:19]
	v_pk_add_f32 v[162:163], v[214:215], v[162:163]
	v_cndmask_b32_e64 v201, v215, 0, s[6:7]
	v_pk_add_f32 v[162:163], v[216:217], v[162:163]
	v_cndmask_b32_e64 v203, 0, v215, s[6:7]
	v_pk_add_f32 v[130:131], v[130:131], v[162:163]
	v_cndmask_b32_e64 v204, v217, 0, s[8:9]
	v_cndmask_b32_e64 v205, 0, v217, s[8:9]
	v_cvt_pk_bf16_f32 v198, v198, v199
	v_cvt_pk_bf16_f32 v199, v201, v204
	v_cvt_pk_bf16_f32 v200, v202, v200
	v_cvt_pk_bf16_f32 v201, v203, v205
	s_nop 0
	s_waitcnt lgkmcnt(11)
	v_mfma_f32_16x16x32_bf16 v[44:47], v[158:161], v[198:201], v[44:47]
	s_waitcnt lgkmcnt(10)
	v_mfma_f32_16x16x32_bf16 v[40:43], v[166:169], v[198:201], v[40:43]
	s_waitcnt lgkmcnt(9)
	v_mfma_f32_16x16x32_bf16 v[36:39], v[170:173], v[198:201], v[36:39]
	s_waitcnt lgkmcnt(8)
	v_mfma_f32_16x16x32_bf16 v[32:35], v[174:177], v[198:201], v[32:35]
	s_nop 0
	ds_read2_b64 v[158:161], v181 offset0:134 offset1:138
	ds_read2_b64 v[166:169], v218 offset0:166 offset1:170
	ds_read2_b64 v[170:173], v219 offset0:198 offset1:202
	ds_read2_b64 v[174:177], v220 offset0:134 offset1:138
	ds_read_b128 v[198:201], v119 offset:4608
	ds_read_b128 v[202:205], v119 offset:4672
	v_add_u32_e32 v119, v148, v151
	ds_read_b128 v[206:209], v119
	ds_read_b128 v[210:213], v119 offset:64
	v_add_u32_e32 v119, s70, v154
	v_add_u32_sdwa v162, s70, v144 dst_sel:DWORD dst_unused:UNUSED_PAD src0_sel:DWORD src1_sel:BYTE_1
	v_add_u32_sdwa v163, s70, v145 dst_sel:DWORD dst_unused:UNUSED_PAD src0_sel:DWORD src1_sel:BYTE_2
	v_add_u32_sdwa v178, s70, v145 dst_sel:DWORD dst_unused:UNUSED_PAD src0_sel:DWORD src1_sel:BYTE_3
	ds_read_b32 v119, v119 offset:41856
	ds_read_b32 v179, v162 offset:41856
	ds_read_b32 v214, v163 offset:41856
	ds_read_b32 v215, v178 offset:41856
	s_nop 0
	s_waitcnt vmcnt(3) lgkmcnt(14)
	v_mfma_f32_16x16x32_bf16 v[182:185], v[182:185], v[96:99], 0
	s_waitcnt vmcnt(2)
	v_mfma_f32_16x16x32_bf16 v[182:185], v[186:189], v[100:103], v[182:185]
	v_mfma_f32_16x16x32_bf16 v[186:189], v[190:193], v[96:99], 0
	v_mfma_f32_16x16x32_bf16 v[186:189], v[194:197], v[100:103], v[186:189]
	s_nop 0
	s_nop 6
	v_cndmask_b32_e64 v162, v186, v182, s[2:3]
	v_add_f32_e32 v136, v136, v162
	v_exp_f32_e32 v162, v136
	v_cndmask_b32_e64 v136, v187, v183, s[4:5]
	v_cndmask_b32_e64 v183, v184, v188, s[22:23]
	s_waitcnt lgkmcnt(13)
	v_add_f32_e32 v165, v165, v183
	v_exp_f32_e32 v190, v165
	v_cndmask_b32_e64 v165, v185, v189, s[24:25]
	v_add_f32_e32 v136, v223, v136
	s_waitcnt lgkmcnt(12)
	v_add_f32_e32 v165, v224, v165
	v_exp_f32_e32 v178, v136
	v_exp_f32_e32 v192, v165
	v_cndmask_b32_e64 v183, v190, 0, s[22:23]
	v_cndmask_b32_e64 v185, 0, v190, s[22:23]
	v_cndmask_b32_e64 v182, 0, v178, s[4:5]
	v_cndmask_b32_e64 v184, v192, 0, s[24:25]
	v_cndmask_b32_e64 v136, 0, v162, s[2:3]
	v_cndmask_b32_e64 v163, v162, 0, s[2:3]
	v_cndmask_b32_e64 v165, v178, 0, s[4:5]
	v_cndmask_b32_e64 v186, 0, v192, s[24:25]
	v_cvt_pk_bf16_f32 v182, v136, v182
	v_cvt_pk_bf16_f32 v183, v183, v184
	v_cvt_pk_bf16_f32 v184, v163, v165
	v_cvt_pk_bf16_f32 v185, v185, v186
	s_nop 0
	s_waitcnt lgkmcnt(11)
	v_mfma_f32_16x16x32_bf16 v[28:31], v[158:161], v[182:185], v[28:31]
	s_waitcnt lgkmcnt(10)
	v_mfma_f32_16x16x32_bf16 v[24:27], v[166:169], v[182:185], v[24:27]
	s_waitcnt lgkmcnt(9)
	v_mfma_f32_16x16x32_bf16 v[20:23], v[170:173], v[182:185], v[20:23]
	s_waitcnt lgkmcnt(8)
	v_mfma_f32_16x16x32_bf16 v[16:19], v[174:177], v[182:185], v[16:19]
	s_nop 0
	ds_read2_b64 v[158:161], v220 offset0:136 offset1:140
	ds_read2_b64 v[166:169], v219 offset0:200 offset1:204
	ds_read2_b64 v[170:173], v218 offset0:168 offset1:172
	ds_read2_b64 v[174:177], v181 offset0:136 offset1:140
	s_nop 0
	s_waitcnt vmcnt(1) lgkmcnt(11)
	v_mfma_f32_16x16x32_bf16 v[182:185], v[198:201], v[104:107], 0
	s_waitcnt lgkmcnt(9)
	v_mfma_f32_16x16x32_bf16 v[186:189], v[206:209], v[104:107], 0
	s_waitcnt vmcnt(0)
	v_mfma_f32_16x16x32_bf16 v[182:185], v[202:205], v[108:111], v[182:185]
	s_waitcnt lgkmcnt(8)
	v_mfma_f32_16x16x32_bf16 v[186:189], v[210:213], v[108:111], v[186:189]
	s_nop 0
	s_nop 6
	v_cndmask_b32_e64 v136, v182, v186, s[26:27]
	s_waitcnt lgkmcnt(7)
	v_add_f32_e32 v119, v119, v136
	v_exp_f32_e32 v163, v119
	v_cndmask_b32_e64 v119, v183, v187, s[28:29]
	v_cndmask_b32_e64 v181, v184, v188, s[30:31]
	s_waitcnt lgkmcnt(6)
	v_add_f32_e32 v119, v179, v119
	s_waitcnt lgkmcnt(5)
	v_add_f32_e32 v181, v214, v181
	v_exp_f32_e32 v179, v119
	v_exp_f32_e32 v191, v181
	v_cndmask_b32_e64 v181, v185, v189, s[34:35]
	s_waitcnt lgkmcnt(4)
	v_add_f32_e32 v181, v215, v181
	v_exp_f32_e32 v193, v181
	v_cndmask_b32_e64 v119, v163, 0, s[26:27]
	v_cndmask_b32_e64 v136, 0, v163, s[26:27]
	v_pk_add_f32 v[162:163], v[162:163], 0 op_sel_hi:[1,0]
	v_cndmask_b32_e64 v183, v191, 0, s[30:31]
	v_pk_add_f32 v[162:163], v[178:179], v[162:163]
	v_cndmask_b32_e64 v185, 0, v191, s[30:31]
	v_pk_add_f32 v[162:163], v[190:191], v[162:163]
	v_cndmask_b32_e64 v184, v193, 0, s[34:35]
	v_pk_add_f32 v[162:163], v[192:193], v[162:163]
	v_cndmask_b32_e64 v165, v179, 0, s[28:29]
	v_pk_add_f32 v[124:125], v[124:125], v[162:163]
	v_cndmask_b32_e64 v181, 0, v179, s[28:29]
	v_cndmask_b32_e64 v186, 0, v193, s[34:35]
	v_cvt_pk_bf16_f32 v182, v119, v165
	v_cvt_pk_bf16_f32 v183, v183, v184
	v_cvt_pk_bf16_f32 v184, v136, v181
	v_cvt_pk_bf16_f32 v185, v185, v186
	s_nop 0
	s_waitcnt lgkmcnt(0)
	v_mfma_f32_16x16x32_bf16 v[12:15], v[174:177], v[182:185], v[12:15]
	v_mfma_f32_16x16x32_bf16 v[8:11], v[170:173], v[182:185], v[8:11]
	v_mfma_f32_16x16x32_bf16 v[4:7], v[166:169], v[182:185], v[4:7]
	v_mfma_f32_16x16x32_bf16 v[0:3], v[158:161], v[182:185], v[0:3]
	s_nop 0

.LBB0_412:
	s_add_i32 s68, s60, -2
	s_cmp_ge_u32 s68, s38
	s_cselect_b64 s[72:73], -1, 0
	s_cmp_lt_u32 s68, s39
	s_cselect_b64 vcc, -1, 0
	s_and_b64 s[72:73], s[72:73], vcc
	s_andn2_b64 vcc, exec, s[72:73]
	s_cbranch_vccnz .LBB0_414
	v_add_u32_e32 v178, v150, v149
	v_add_u32_e32 v181, 0x6800, v178
	v_add_u32_e32 v218, 0x7000, v178
	v_add_u32_e32 v219, 0x7800, v178
	v_add_u32_e32 v178, v150, v151
	v_add_u32_e32 v119, v148, v149
	v_add_u32_e32 v136, s70, v152
	v_add_u32_sdwa v163, s70, v143 dst_sel:DWORD dst_unused:UNUSED_PAD src0_sel:DWORD src1_sel:BYTE_2
	v_add_u32_sdwa v165, s70, v143 dst_sel:DWORD dst_unused:UNUSED_PAD src0_sel:DWORD src1_sel:BYTE_3
	v_add_u32_e32 v220, 0x6800, v178
	v_add_u32_sdwa v179, s70, v141 dst_sel:DWORD dst_unused:UNUSED_PAD src0_sel:DWORD src1_sel:BYTE_1
	ds_read_b128 v[158:161], v119 offset:18432
	ds_read_b128 v[166:169], v119 offset:18496
	ds_read_b128 v[170:173], v119 offset:20736
	ds_read_b128 v[174:177], v119 offset:20800
	v_add_u32_e32 v162, s70, v153
	ds_read2_b64 v[182:185], v181 offset0:128 offset1:132
	ds_read2_b64 v[186:189], v218 offset0:160 offset1:164
	ds_read2_b64 v[190:193], v219 offset0:192 offset1:196
	ds_read2_b64 v[194:197], v220 offset0:128 offset1:132
	ds_read_b128 v[198:201], v119 offset:19584
	ds_read_b128 v[202:205], v119 offset:19648
	ds_read_b128 v[206:209], v119 offset:21888
	ds_read_b128 v[210:213], v119 offset:21952
	v_add_u32_e32 v178, s70, v155
	v_add_u32_sdwa v214, s70, v142 dst_sel:DWORD dst_unused:UNUSED_PAD src0_sel:DWORD src1_sel:BYTE_2
	v_add_u32_sdwa v215, s70, v142 dst_sel:DWORD dst_unused:UNUSED_PAD src0_sel:DWORD src1_sel:BYTE_3
	ds_read_b32 v136, v136 offset:41984
	ds_read_b32 v216, v162 offset:41984
	ds_read_b32 v163, v163 offset:41984
	ds_read_b32 v165, v165 offset:41984
	ds_read_b32 v217, v178 offset:41984
	ds_read_b32 v179, v179 offset:41984
	ds_read_b32 v221, v214 offset:41984
	ds_read_b32 v222, v215 offset:41984
	s_nop 0
	s_waitcnt vmcnt(7) lgkmcnt(14)
	v_mfma_f32_16x16x32_bf16 v[158:161], v[158:161], v[80:83], 0
	s_waitcnt vmcnt(6)
	v_mfma_f32_16x16x32_bf16 v[158:161], v[166:169], v[84:87], v[158:161]
	v_mfma_f32_16x16x32_bf16 v[166:169], v[170:173], v[80:83], 0
	v_mfma_f32_16x16x32_bf16 v[166:169], v[174:177], v[84:87], v[166:169]
	s_nop 0
	s_nop 6
	v_cndmask_b32_e64 v158, v166, v158, s[20:21]
	s_waitcnt lgkmcnt(7)
	v_add_f32_e32 v136, v136, v158
	v_exp_f32_e32 v162, v136
	v_cndmask_b32_e64 v136, v159, v167, s[10:11]
	v_cndmask_b32_e64 v159, v160, v168, s[12:13]
	s_waitcnt lgkmcnt(5)
	v_add_f32_e32 v159, v163, v159
	v_add_f32_e32 v136, v216, v136
	v_exp_f32_e32 v214, v159
	v_cndmask_b32_e64 v159, v161, v169, s[14:15]
	v_exp_f32_e32 v178, v136
	s_waitcnt lgkmcnt(4)
	v_add_f32_e32 v159, v165, v159
	v_exp_f32_e32 v216, v159
	v_cndmask_b32_e64 v159, v214, 0, s[12:13]
	v_cndmask_b32_e64 v158, v178, 0, s[10:11]
	v_cndmask_b32_e64 v160, 0, v178, s[10:11]
	v_cndmask_b32_e64 v161, 0, v214, s[12:13]
	v_cndmask_b32_e64 v136, 0, v162, s[20:21]
	v_cndmask_b32_e64 v166, v162, 0, s[20:21]
	v_cndmask_b32_e64 v163, v216, 0, s[14:15]
	v_cndmask_b32_e64 v165, 0, v216, s[14:15]
	v_cvt_pk_bf16_f32 v158, v136, v158
	v_cvt_pk_bf16_f32 v159, v159, v163
	v_cvt_pk_bf16_f32 v160, v166, v160
	v_cvt_pk_bf16_f32 v161, v161, v165
	s_nop 0
	v_mfma_f32_16x16x32_bf16 v[60:63], v[182:185], v[158:161], v[60:63]
	v_mfma_f32_16x16x32_bf16 v[56:59], v[186:189], v[158:161], v[56:59]
	v_mfma_f32_16x16x32_bf16 v[52:55], v[190:193], v[158:161], v[52:55]
	v_mfma_f32_16x16x32_bf16 v[48:51], v[194:197], v[158:161], v[48:51]
	s_nop 0
	ds_read2_b64 v[158:161], v181 offset0:130 offset1:134
	ds_read2_b64 v[166:169], v218 offset0:162 offset1:166
	ds_read2_b64 v[170:173], v219 offset0:194 offset1:198
	ds_read2_b64 v[174:177], v220 offset0:130 offset1:134
	ds_read_b128 v[182:185], v119 offset:21888
	ds_read_b128 v[186:189], v119 offset:21952
	ds_read_b128 v[190:193], v119 offset:24192
	ds_read_b128 v[194:197], v119 offset:24256
	v_add_u32_e32 v136, s70, v156
	v_add_u32_sdwa v165, s70, v140 dst_sel:DWORD dst_unused:UNUSED_PAD src0_sel:DWORD src1_sel:BYTE_2
	v_add_u32_sdwa v163, s70, v139 dst_sel:DWORD dst_unused:UNUSED_PAD src0_sel:DWORD src1_sel:BYTE_1
	v_add_u32_sdwa v215, s70, v140 dst_sel:DWORD dst_unused:UNUSED_PAD src0_sel:DWORD src1_sel:BYTE_3
	ds_read_b32 v136, v136 offset:41984
	ds_read_b32 v223, v163 offset:41984
	ds_read_b32 v165, v165 offset:41984
	ds_read_b32 v224, v215 offset:41984
	s_nop 0
	s_waitcnt vmcnt(5)
	v_mfma_f32_16x16x32_bf16 v[198:201], v[198:201], v[88:91], 0
	s_waitcnt vmcnt(4)
	v_mfma_f32_16x16x32_bf16 v[198:201], v[202:205], v[92:95], v[198:201]
	v_mfma_f32_16x16x32_bf16 v[202:205], v[206:209], v[88:91], 0
	v_mfma_f32_16x16x32_bf16 v[202:205], v[210:213], v[92:95], v[202:205]
	s_nop 0
	s_nop 6
	v_cndmask_b32_e64 v163, v198, v202, s[16:17]
	s_waitcnt lgkmcnt(14)
	v_add_f32_e32 v163, v217, v163
	v_cndmask_b32_e64 v198, v199, v203, s[18:19]
	v_cndmask_b32_e64 v200, v200, v204, s[6:7]
	v_exp_f32_e32 v163, v163
	v_add_f32_e32 v179, v179, v198
	s_waitcnt lgkmcnt(13)
	v_add_f32_e32 v200, v221, v200
	v_exp_f32_e32 v179, v179
	v_exp_f32_e32 v215, v200
	v_cndmask_b32_e64 v200, v201, v205, s[8:9]
	s_waitcnt lgkmcnt(12)
	v_add_f32_e32 v200, v222, v200
	v_exp_f32_e32 v217, v200
	v_cndmask_b32_e64 v198, v163, 0, s[16:17]
	v_cndmask_b32_e64 v202, 0, v163, s[16:17]
	v_pk_add_f32 v[162:163], v[162:163], 0 op_sel_hi:[1,0]
	v_cndmask_b32_e64 v199, v179, 0, s[18:19]
	v_pk_add_f32 v[162:163], v[178:179], v[162:163]
	v_cndmask_b32_e64 v200, 0, v179, s[18:19]
	v_pk_add_f32 v[162:163], v[214:215], v[162:163]
	v_cndmask_b32_e64 v201, v215, 0, s[6:7]
	v_pk_add_f32 v[162:163], v[216:217], v[162:163]
	v_cndmask_b32_e64 v203, 0, v215, s[6:7]
	v_pk_add_f32 v[130:131], v[130:131], v[162:163]
	v_cndmask_b32_e64 v204, v217, 0, s[8:9]
	v_cndmask_b32_e64 v205, 0, v217, s[8:9]
	v_cvt_pk_bf16_f32 v198, v198, v199
	v_cvt_pk_bf16_f32 v199, v201, v204
	v_cvt_pk_bf16_f32 v200, v202, v200
	v_cvt_pk_bf16_f32 v201, v203, v205
	s_nop 0
	s_waitcnt lgkmcnt(11)
	v_mfma_f32_16x16x32_bf16 v[44:47], v[158:161], v[198:201], v[44:47]
	s_waitcnt lgkmcnt(10)
	v_mfma_f32_16x16x32_bf16 v[40:43], v[166:169], v[198:201], v[40:43]
	s_waitcnt lgkmcnt(9)
	v_mfma_f32_16x16x32_bf16 v[36:39], v[170:173], v[198:201], v[36:39]
	s_waitcnt lgkmcnt(8)
	v_mfma_f32_16x16x32_bf16 v[32:35], v[174:177], v[198:201], v[32:35]
	s_nop 0
	ds_read2_b64 v[158:161], v181 offset0:134 offset1:138
	ds_read2_b64 v[166:169], v218 offset0:166 offset1:170
	ds_read2_b64 v[170:173], v219 offset0:198 offset1:202
	ds_read2_b64 v[174:177], v220 offset0:134 offset1:138
	ds_read_b128 v[198:201], v119 offset:23040
	ds_read_b128 v[202:205], v119 offset:23104
	v_add_u32_e32 v119, v148, v151
	ds_read_b128 v[206:209], v119 offset:18432
	ds_read_b128 v[210:213], v119 offset:18496
	v_add_u32_e32 v119, s70, v154
	v_add_u32_sdwa v162, s70, v144 dst_sel:DWORD dst_unused:UNUSED_PAD src0_sel:DWORD src1_sel:BYTE_1
	v_add_u32_sdwa v163, s70, v145 dst_sel:DWORD dst_unused:UNUSED_PAD src0_sel:DWORD src1_sel:BYTE_2
	v_add_u32_sdwa v178, s70, v145 dst_sel:DWORD dst_unused:UNUSED_PAD src0_sel:DWORD src1_sel:BYTE_3
	ds_read_b32 v119, v119 offset:41984
	ds_read_b32 v179, v162 offset:41984
	ds_read_b32 v214, v163 offset:41984
	ds_read_b32 v215, v178 offset:41984
	s_nop 0
	s_waitcnt vmcnt(3) lgkmcnt(14)
	v_mfma_f32_16x16x32_bf16 v[182:185], v[182:185], v[96:99], 0
	s_waitcnt vmcnt(2)
	v_mfma_f32_16x16x32_bf16 v[182:185], v[186:189], v[100:103], v[182:185]
	v_mfma_f32_16x16x32_bf16 v[186:189], v[190:193], v[96:99], 0
	v_mfma_f32_16x16x32_bf16 v[186:189], v[194:197], v[100:103], v[186:189]
	s_nop 0
	s_nop 6
	v_cndmask_b32_e64 v162, v186, v182, s[2:3]
	v_add_f32_e32 v136, v136, v162
	v_exp_f32_e32 v162, v136
	v_cndmask_b32_e64 v136, v187, v183, s[4:5]
	v_cndmask_b32_e64 v183, v184, v188, s[22:23]
	s_waitcnt lgkmcnt(13)
	v_add_f32_e32 v165, v165, v183
	v_exp_f32_e32 v190, v165
	v_cndmask_b32_e64 v165, v185, v189, s[24:25]
	v_add_f32_e32 v136, v223, v136
	s_waitcnt lgkmcnt(12)
	v_add_f32_e32 v165, v224, v165
	v_exp_f32_e32 v178, v136
	v_exp_f32_e32 v192, v165
	v_cndmask_b32_e64 v183, v190, 0, s[22:23]
	v_cndmask_b32_e64 v185, 0, v190, s[22:23]
	v_cndmask_b32_e64 v182, 0, v178, s[4:5]
	v_cndmask_b32_e64 v184, v192, 0, s[24:25]
	v_cndmask_b32_e64 v136, 0, v162, s[2:3]
	v_cndmask_b32_e64 v163, v162, 0, s[2:3]
	v_cndmask_b32_e64 v165, v178, 0, s[4:5]
	v_cndmask_b32_e64 v186, 0, v192, s[24:25]
	v_cvt_pk_bf16_f32 v182, v136, v182
	v_cvt_pk_bf16_f32 v183, v183, v184
	v_cvt_pk_bf16_f32 v184, v163, v165
	v_cvt_pk_bf16_f32 v185, v185, v186
	s_nop 0
	s_waitcnt lgkmcnt(11)
	v_mfma_f32_16x16x32_bf16 v[28:31], v[158:161], v[182:185], v[28:31]
	s_waitcnt lgkmcnt(10)
	v_mfma_f32_16x16x32_bf16 v[24:27], v[166:169], v[182:185], v[24:27]
	s_waitcnt lgkmcnt(9)
	v_mfma_f32_16x16x32_bf16 v[20:23], v[170:173], v[182:185], v[20:23]
	s_waitcnt lgkmcnt(8)
	v_mfma_f32_16x16x32_bf16 v[16:19], v[174:177], v[182:185], v[16:19]
	s_nop 0
	ds_read2_b64 v[158:161], v220 offset0:136 offset1:140
	ds_read2_b64 v[166:169], v219 offset0:200 offset1:204
	ds_read2_b64 v[170:173], v218 offset0:168 offset1:172
	ds_read2_b64 v[174:177], v181 offset0:136 offset1:140
	s_nop 0
	s_waitcnt vmcnt(1) lgkmcnt(11)
	v_mfma_f32_16x16x32_bf16 v[182:185], v[198:201], v[104:107], 0
	s_waitcnt lgkmcnt(9)
	v_mfma_f32_16x16x32_bf16 v[186:189], v[206:209], v[104:107], 0
	s_waitcnt vmcnt(0)
	v_mfma_f32_16x16x32_bf16 v[182:185], v[202:205], v[108:111], v[182:185]
	s_waitcnt lgkmcnt(8)
	v_mfma_f32_16x16x32_bf16 v[186:189], v[210:213], v[108:111], v[186:189]
	s_nop 0
	s_nop 6
	v_cndmask_b32_e64 v136, v182, v186, s[26:27]
	s_waitcnt lgkmcnt(7)
	v_add_f32_e32 v119, v119, v136
	v_exp_f32_e32 v163, v119
	v_cndmask_b32_e64 v119, v183, v187, s[28:29]
	v_cndmask_b32_e64 v181, v184, v188, s[30:31]
	s_waitcnt lgkmcnt(6)
	v_add_f32_e32 v119, v179, v119
	s_waitcnt lgkmcnt(5)
	v_add_f32_e32 v181, v214, v181
	v_exp_f32_e32 v179, v119
	v_exp_f32_e32 v191, v181
	v_cndmask_b32_e64 v181, v185, v189, s[34:35]
	s_waitcnt lgkmcnt(4)
	v_add_f32_e32 v181, v215, v181
	v_exp_f32_e32 v193, v181
	v_cndmask_b32_e64 v119, v163, 0, s[26:27]
	v_cndmask_b32_e64 v136, 0, v163, s[26:27]
	v_pk_add_f32 v[162:163], v[162:163], 0 op_sel_hi:[1,0]
	v_cndmask_b32_e64 v183, v191, 0, s[30:31]
	v_pk_add_f32 v[162:163], v[178:179], v[162:163]
	v_cndmask_b32_e64 v185, 0, v191, s[30:31]
	v_pk_add_f32 v[162:163], v[190:191], v[162:163]
	v_cndmask_b32_e64 v184, v193, 0, s[34:35]
	v_pk_add_f32 v[162:163], v[192:193], v[162:163]
	v_cndmask_b32_e64 v165, v179, 0, s[28:29]
	v_pk_add_f32 v[124:125], v[124:125], v[162:163]
	v_cndmask_b32_e64 v181, 0, v179, s[28:29]
	v_cndmask_b32_e64 v186, 0, v193, s[34:35]
	v_cvt_pk_bf16_f32 v182, v119, v165
	v_cvt_pk_bf16_f32 v183, v183, v184
	v_cvt_pk_bf16_f32 v184, v136, v181
	v_cvt_pk_bf16_f32 v185, v185, v186
	s_nop 0
	s_waitcnt lgkmcnt(0)
	v_mfma_f32_16x16x32_bf16 v[12:15], v[174:177], v[182:185], v[12:15]
	v_mfma_f32_16x16x32_bf16 v[8:11], v[170:173], v[182:185], v[8:11]
	v_mfma_f32_16x16x32_bf16 v[4:7], v[166:169], v[182:185], v[4:7]
	v_mfma_f32_16x16x32_bf16 v[0:3], v[158:161], v[182:185], v[0:3]
	s_nop 0

.LBB0_464:
	s_andn2_b64 vcc, exec, s[48:49]
	s_cbranch_vccnz .LBB0_509
	s_mul_i32 s4, s92, 0x1d1
	v_lshrrev_b32_e32 v0, 5, v180
	v_and_b32_e32 v7, 31, v180
	v_mul_u32_u24_e32 v0, 31, v0
	v_add3_u32 v0, s4, v0, v7
	v_lshlrev_b32_e32 v0, 2, v0
	v_cmp_ne_u32_e32 vcc, 31, v7
	v_lshlrev_b32_e32 v16, 2, v180
	v_mov_b32_e32 v20, 0
	v_mov_b32_e32 v21, 0
	v_mov_b32_e32 v22, 0
	v_mov_b32_e32 v23, 0
	v_mov_b32_e32 v24, 0
	v_mov_b32_e32 v25, 0
	v_mov_b32_e32 v26, 0
	v_mov_b32_e32 v27, 0
	s_waitcnt lgkmcnt(0)
	global_load_dword v2, v16, s[40:41]
	global_load_dword v3, v16, s[42:43]
	s_mov_b64 s[2:3], exec
	v_cmp_gt_u32_e64 s[0:1], 32, v180
	s_and_b64 exec, exec, vcc
	global_load_dword v20, v0, s[46:47]
	global_load_dword v21, v0, s[46:47] offset:248
	global_load_dword v22, v0, s[46:47] offset:496
	global_load_dword v23, v0, s[46:47] offset:744
	global_load_dword v24, v0, s[46:47] offset:992
	global_load_dword v25, v0, s[46:47] offset:1240
	global_load_dword v26, v0, s[46:47] offset:1488
	s_and_b64 exec, exec, s[0:1]
	global_load_dword v27, v0, s[46:47] offset:1736
	s_mov_b64 exec, s[2:3]
	v_xor_b32_e32 v8, 1, v180
	v_lshlrev_b32_e32 v8, 2, v8
	v_xor_b32_e32 v9, 2, v180
	v_lshlrev_b32_e32 v9, 2, v9
	v_xor_b32_e32 v10, 4, v180
	v_lshlrev_b32_e32 v10, 2, v10
	v_xor_b32_e32 v11, 8, v180
	v_lshlrev_b32_e32 v11, 2, v11
	v_xor_b32_e32 v137, 16, v180
	v_lshlrev_b32_e32 v137, 2, v137
	v_xor_b32_e32 v138, 32, v180
	v_lshlrev_b32_e32 v138, 2, v138
	s_mul_i32 s5, s92, 0x780
	v_add_u32_e32 v16, s5, v16
	v_add_u32_e32 v16, 0xa000, v16
	s_waitcnt vmcnt(8)
	v_max_f32_e64 v5, |v2|, |v2|
	v_max_f32_e64 v6, |v3|, |v3|
	s_waitcnt vmcnt(0)
	v_max_f32_e64 v1, |v20|, |v21|
	v_max_f32_e64 v4, |v22|, |v23|
	v_max_f32_e64 v12, |v24|, |v25|
	v_max_f32_e64 v13, |v26|, |v27|
	v_max_f32_e32 v1, v1, v4
	v_max_f32_e32 v12, v12, v13
	v_max_f32_e32 v1, v1, v12
	ds_bpermute_b32 v12, v8, v1
	ds_bpermute_b32 v13, v8, v5
	ds_bpermute_b32 v14, v8, v6
	s_waitcnt lgkmcnt(0)
	v_max_f32_e32 v1, v1, v12
	v_max_f32_e32 v5, v5, v13
	v_max_f32_e32 v6, v6, v14
	ds_bpermute_b32 v12, v9, v1
	ds_bpermute_b32 v13, v9, v5
	ds_bpermute_b32 v14, v9, v6
	s_waitcnt lgkmcnt(0)
	v_max_f32_e32 v1, v1, v12
	v_max_f32_e32 v5, v5, v13
	v_max_f32_e32 v6, v6, v14
	ds_bpermute_b32 v12, v10, v1
	ds_bpermute_b32 v13, v10, v5
	ds_bpermute_b32 v14, v10, v6
	s_waitcnt lgkmcnt(0)
	v_max_f32_e32 v1, v1, v12
	v_max_f32_e32 v5, v5, v13
	v_max_f32_e32 v6, v6, v14
	ds_bpermute_b32 v12, v11, v1
	ds_bpermute_b32 v13, v11, v5
	ds_bpermute_b32 v14, v11, v6
	s_waitcnt lgkmcnt(0)
	v_max_f32_e32 v1, v1, v12
	v_max_f32_e32 v5, v5, v13
	v_max_f32_e32 v6, v6, v14
	ds_bpermute_b32 v12, v137, v1
	ds_bpermute_b32 v13, v137, v5
	ds_bpermute_b32 v14, v137, v6
	s_waitcnt lgkmcnt(0)
	v_max_f32_e32 v1, v1, v12
	v_max_f32_e32 v5, v5, v13
	v_max_f32_e32 v6, v6, v14
	ds_bpermute_b32 v12, v138, v1
	ds_bpermute_b32 v13, v138, v5
	ds_bpermute_b32 v14, v138, v6
	s_waitcnt lgkmcnt(0)
	v_max_f32_e32 v1, v1, v12
	v_max_f32_e32 v5, v5, v13
	v_max_f32_e32 v6, v6, v14
	v_mul_f32_e32 v5, 0x41000000, v5
	v_fmac_f32_e32 v1, v6, v5
	v_mov_b32_e32 v15, 0xf149f2ca
	v_sub_f32_e32 v12, v20, v1
	v_mul_f32_e32 v12, 0x3fb8aa3b, v12
	v_cndmask_b32_e32 v12, v15, v12, vcc
	ds_write_b32 v16, v12
	v_sub_f32_e32 v12, v21, v1
	v_mul_f32_e32 v12, 0x3fb8aa3b, v12
	v_cndmask_b32_e32 v12, v15, v12, vcc
	ds_write_b32 v16, v12 offset:256
	v_sub_f32_e32 v12, v22, v1
	v_mul_f32_e32 v12, 0x3fb8aa3b, v12
	v_cndmask_b32_e32 v12, v15, v12, vcc
	ds_write_b32 v16, v12 offset:512
	v_sub_f32_e32 v12, v23, v1
	v_mul_f32_e32 v12, 0x3fb8aa3b, v12
	v_cndmask_b32_e32 v12, v15, v12, vcc
	ds_write_b32 v16, v12 offset:768
	v_sub_f32_e32 v12, v24, v1
	v_mul_f32_e32 v12, 0x3fb8aa3b, v12
	v_cndmask_b32_e32 v12, v15, v12, vcc
	ds_write_b32 v16, v12 offset:1024
	v_sub_f32_e32 v12, v25, v1
	v_mul_f32_e32 v12, 0x3fb8aa3b, v12
	v_cndmask_b32_e32 v12, v15, v12, vcc
	ds_write_b32 v16, v12 offset:1280
	v_sub_f32_e32 v12, v26, v1
	v_mul_f32_e32 v12, 0x3fb8aa3b, v12
	v_cndmask_b32_e32 v12, v15, v12, vcc
	ds_write_b32 v16, v12 offset:1536
	v_sub_f32_e32 v12, v27, v1
	v_mul_f32_e32 v12, 0x3fb8aa3b, v12
	v_cndmask_b32_e32 v12, v15, v12, vcc
	s_and_b64 exec, exec, s[0:1]
	ds_write_b32 v16, v12 offset:1792
	s_mov_b64 exec, s[2:3]
	s_cmp_ge_u32 s92, 4
	s_cbranch_scc0 .Lprio_a1
	s_setprio 1
.Lprio_a1:
	s_mov_b64 s[2:3], -1
.LBB0_471:
	s_or_b64 exec, exec, s[2:3]
	s_abs_i32 s0, s84
	v_cvt_f32_u32_e32 v0, s0
	s_sub_i32 s3, 0, s0
	s_add_i32 s1, s84, 0x4ff
	s_xor_b32 s2, s1, s84
	v_rcp_iflag_f32_e32 v0, v0
	s_abs_i32 s1, s1
	s_ashr_i32 s2, s2, 31
	s_mov_b32 s49, 0
	v_mul_f32_e32 v0, 0x4f7ffffe, v0
	v_cvt_u32_f32_e32 v0, v0
	s_waitcnt lgkmcnt(0)
	s_barrier
	v_readfirstlane_b32 s4, v0
	s_mul_i32 s3, s3, s4
	s_mul_hi_u32 s3, s4, s3
	s_add_i32 s4, s4, s3
	s_mul_hi_u32 s3, s1, s4
	s_mul_i32 s4, s3, s0
	s_sub_i32 s1, s1, s4
	s_add_i32 s5, s3, 1
	s_sub_i32 s4, s1, s0
	s_cmp_ge_u32 s1, s0
	s_cselect_b32 s3, s5, s3
	s_cselect_b32 s1, s4, s1
	s_add_i32 s4, s3, 1
	s_cmp_ge_u32 s1, s0
	s_cselect_b32 s0, s4, s3
	s_xor_b32 s0, s0, s2
	s_sub_i32 s0, s0, s2
	s_mul_i32 s70, s0, s33
	s_min_i32 s0, s0, 3
	s_add_i32 s0, s70, s0
	s_min_i32 s71, s0, 0x500
	s_cmp_lt_i32 s70, s71
	s_cbranch_scc0 .LBB0_508
	v_lshrrev_b32_e32 v1, 2, v180
	v_and_b32_e32 v2, 12, v1
	v_add_u32_e32 v13, 26, v2
	v_add_u32_e32 v14, 24, v146
	v_sub_u32_e32 v15, v13, v14
	v_mov_b32_e32 v16, 0x400
	v_cmp_gt_u32_e32 vcc, 16, v15
	v_mov_b32_e32 v18, 0x800
	v_mov_b32_e32 v19, 0x200
	v_cndmask_b32_e32 v15, 0, v16, vcc
	v_add_u32_e32 v16, 27, v2
	v_sub_u32_e32 v17, v16, v14
	v_cmp_gt_u32_e64 s[0:1], 16, v17
	v_sub_u32_e64 v0, v146, 8 clamp
	v_or_b32_e32 v4, 1, v2
	v_cndmask_b32_e64 v17, 0, v18, s[0:1]
	v_add_u32_e32 v18, 25, v2
	v_sub_u32_e32 v14, v18, v14
	v_cmp_gt_u32_e64 s[4:5], 16, v14
	v_or_b32_e32 v6, 2, v2
	v_or_b32_e32 v8, 3, v1
	v_add_u32_e32 v9, 8, v146
	v_add_u32_e32 v11, 9, v2
	v_cndmask_b32_e64 v14, 0, v19, s[4:5]
	v_add_u32_e32 v19, 10, v2
	v_add_u32_e32 v21, 11, v2
	v_sub_u32_e32 v3, v2, v0
	v_sub_u32_e32 v5, v4, v0
	v_sub_u32_e32 v7, v6, v0
	v_sub_u32_e32 v0, v8, v0
	v_sub_u32_e32 v10, v2, v146
	v_sub_u32_e32 v12, v11, v9
	v_sub_u32_e32 v20, v19, v9
	v_sub_u32_e32 v9, v21, v9
	v_mov_b32_e32 v22, 0x80
	v_cmp_lt_u32_e64 s[8:9], 15, v9
	v_cmp_lt_u32_e64 s[14:15], 15, v0
	v_cmp_lt_u32_e64 s[16:17], 15, v10
	v_cmp_gt_u32_e64 s[2:3], 16, v10
	v_cmp_lt_u32_e64 s[6:7], 15, v20
	v_cndmask_b32_e64 v9, v22, 0, s[8:9]
	v_cmp_lt_u32_e64 s[10:11], 15, v5
	v_cndmask_b32_e64 v0, 8, 0, s[14:15]
	v_cndmask_b32_e64 v10, 16, 0, s[16:17]
	v_cndmask_b32_e64 v20, 64, 0, s[6:7]
	v_cndmask_b32_e64 v5, 2, 0, s[10:11]
	v_cmp_lt_u32_e64 s[12:13], 15, v7
	v_cmp_lt_u32_e64 s[18:19], 15, v12
	v_or3_b32 v0, v0, v10, v9
	v_or_b32_e32 v15, v15, v17
	v_mov_b32_e32 v17, 0x100
	v_cndmask_b32_e64 v7, 4, 0, s[12:13]
	v_cndmask_b32_e64 v12, 32, 0, s[18:19]
	v_or3_b32 v0, v5, v20, v0
	v_cndmask_b32_e64 v17, 0, v17, s[2:3]
	v_or3_b32 v0, v7, v12, v0
	v_or3_b32 v5, v17, v0, v14
	v_add_u32_e32 v0, 42, v2
	v_add_u32_e32 v12, 43, v2
	v_add_u32_e32 v17, 41, v2
	v_cndmask_b32_e32 v0, v0, v13, vcc
	v_or_b32_e32 v9, 32, v146
	v_cndmask_b32_e64 v12, v12, v16, s[0:1]
	v_cndmask_b32_e64 v17, v17, v18, s[4:5]
	v_sub_u32_e32 v0, v0, v9
	v_sub_u32_e32 v12, v12, v9
	v_sub_u32_e32 v17, v17, v9
	v_cndmask_b32_e64 v22, 40, 24, s[2:3]
	v_sub_u32_e32 v9, v2, v9
	v_mov_b32_e32 v20, 0x3c00
	v_add_u32_e32 v9, v9, v22
	v_mov_b32_e32 v10, 0x3c0000
	v_bfrev_b32_e32 v14, 60
	v_lshl_add_u32 v17, v17, 10, v20
	v_lshl_add_u32 v9, v9, 2, 60
	v_lshl_add_u32 v0, v0, 18, v10
	v_lshl_add_u32 v12, v12, 26, v14
	v_or_b32_e32 v139, v17, v9
	v_or3_b32 v140, v0, v12, v139
	v_cndmask_b32_e64 v0, v19, v13, s[6:7]
	v_or_b32_e32 v9, 16, v146
	v_cndmask_b32_e64 v12, v21, v16, s[8:9]
	v_cndmask_b32_e64 v11, v11, v18, s[18:19]
	v_sub_u32_e32 v0, v0, v9
	v_sub_u32_e32 v12, v12, v9
	v_sub_u32_e32 v11, v11, v9
	v_cndmask_b32_e64 v13, 8, 24, s[16:17]
	v_sub_u32_e32 v9, v2, v9
	v_add_u32_e32 v9, v9, v13
	v_lshl_add_u32 v11, v11, 10, v20
	v_lshl_add_u32 v9, v9, 2, 60
	v_lshl_add_u32 v0, v0, 18, v10
	v_lshl_add_u32 v12, v12, 26, v14
	v_or_b32_e32 v141, v11, v9
	v_or3_b32 v142, v0, v12, v141
	v_or_b32_e32 v0, 18, v2
	v_cndmask_b32_e64 v0, v6, v0, s[12:13]
	v_or_b32_e32 v6, 19, v1
	v_cndmask_b32_e64 v6, v8, v6, s[14:15]
	v_or_b32_e32 v8, 17, v2
	v_cndmask_b32_e64 v4, v4, v8, s[10:11]
	v_or_b32_e32 v8, 16, v2
	v_cmp_gt_u32_e64 s[20:21], 16, v3
	v_sub_u32_e32 v4, v4, v146
	v_sub_u32_e32 v0, v0, v146
	v_cndmask_b32_e64 v3, v8, v2, s[20:21]
	v_sub_u32_e32 v3, v3, v146
	v_sub_u32_e32 v6, v6, v146
	v_lshl_add_u32 v4, v4, 10, v20
	v_lshl_add_u32 v3, v3, 2, 60
	v_lshl_add_u32 v0, v0, 18, v10
	v_lshl_add_u32 v6, v6, 26, v14
	v_or_b32_e32 v4, v4, v3
	v_or3_b32 v143, v0, v6, v4
	v_or_b32_e32 v6, 48, v180
	v_add_u32_e32 v8, -8, v6
	v_or_b32_e32 v0, 35, v1
	v_min_u32_e32 v8, 48, v8
	v_sub_u32_e32 v9, v0, v8
	v_mov_b32_e32 v11, 0x8000
	v_cmp_gt_u32_e32 vcc, 16, v9
	v_mov_b32_e32 v16, 0x4000
	v_or_b32_e32 v1, 51, v1
	v_cndmask_b32_e32 v9, 0, v11, vcc
	v_or_b32_e32 v11, 34, v2
	v_sub_u32_e32 v12, v11, v8
	v_cmp_gt_u32_e64 s[0:1], 16, v12
	v_mov_b32_e32 v18, 0x2000
	v_cndmask_b32_e32 v0, v1, v0, vcc
	v_cndmask_b32_e64 v12, 0, v16, s[0:1]
	v_or_b32_e32 v16, 33, v2
	v_sub_u32_e32 v17, v16, v8
	v_cmp_gt_u32_e64 s[22:23], 16, v17
	v_or_b32_e32 v1, 50, v2
	v_cndmask_b32_e64 v1, v1, v11, s[0:1]
	v_cndmask_b32_e64 v17, 0, v18, s[22:23]
	v_or_b32_e32 v18, 32, v2
	v_sub_u32_e32 v8, v18, v8
	v_sub_u32_e32 v1, v1, v6
	v_cmp_gt_u32_e64 s[24:25], 16, v8
	v_lshl_add_u32 v1, v1, 18, v10
	v_or_b32_e32 v10, 49, v2
	v_or_b32_e32 v2, 48, v2
	v_cndmask_b32_e64 v10, v10, v16, s[22:23]
	v_cndmask_b32_e64 v2, v2, v18, s[24:25]
	v_sub_u32_e32 v10, v10, v6
	v_sub_u32_e32 v2, v2, v6
	v_sub_u32_e32 v0, v0, v6
	v_lshl_add_u32 v10, v10, 10, v20
	v_lshl_add_u32 v2, v2, 2, 60
	v_lshl_add_u32 v0, v0, 26, v14
	v_or_b32_e32 v144, v10, v2
	v_or3_b32 v145, v1, v0, v144
	v_and_b32_e32 v1, 7, v164
	v_mov_b32_e32 v19, 0x1000
	v_lshrrev_b32_e32 v147, 3, v164
	v_lshlrev_b32_e32 v114, 4, v1
	s_movk_i32 s0, 0x90
	s_movk_i32 s26, 0x400
	s_movk_i32 s27, 0x800
	v_cndmask_b32_e64 v8, 0, v19, s[24:25]
	v_lshlrev_b32_e32 v0, 3, v1
	v_lshrrev_b32_e32 v1, 4, v180
	v_mad_u32_u24 v10, v147, s0, v114
	s_add_u32 s0, s80, 0x11000000
	v_and_b32_e32 v112, 48, v180
	v_or_b32_e32 v7, v15, v5
	s_movk_i32 s29, 0x1000
	v_or_b32_e32 v8, v8, v17
	v_lshl_add_u32 v150, v1, 3, 0
	v_mul_u32_u24_e32 v151, 0x90, v6
	v_bitop3_b32 v6, v15, s26, v5 bitop3:0xc8
	v_bitop3_b32 v5, v15, s27, v5 bitop3:0xc8
	v_and_b32_e32 v152, 0xfc, v3
	v_and_b32_e32 v154, 0xfc, v2
	v_lshlrev_b32_e32 v2, 2, v1
	s_addc_u32 s1, s81, 0
	v_lshl_add_u32 v1, v13, 2, v112
	v_lshlrev_b32_e32 v3, 2, v146
	s_movk_i32 s28, 0x2000
	v_cmp_eq_u32_e64 s[24:25], 0, v5
	v_bitop3_b32 v5, v8, s29, v7 bitop3:0xc8
	s_add_u32 s50, s80, 0x50000
	v_sub_u32_e32 v1, v1, v3
	s_movk_i32 s30, 0x4000
	v_or_b32_e32 v17, v8, v7
	v_or_b32_e32 v9, v12, v9
	v_cmp_eq_u32_e64 s[26:27], 0, v5
	v_bitop3_b32 v5, v8, s28, v7 bitop3:0xc8
	s_addc_u32 s51, s81, 0
	v_add_u32_e32 v1, -4, v1
	s_mov_b32 s34, 0x8000
	v_cmp_eq_u32_e64 s[28:29], 0, v5
	v_bitop3_b32 v5, v9, s30, v17 bitop3:0xc8
	s_add_u32 s72, s80, 0x17000000
	v_and_b32_e32 v155, 0xfc, v1
	v_lshl_add_u32 v1, v22, 2, v112
	v_mov_b32_e32 v113, 0
	v_cmp_eq_u32_e64 s[30:31], 0, v5
	v_bitop3_b32 v5, v9, s34, v17 bitop3:0xc8
	s_addc_u32 s73, s81, 0
	v_sub_u32_e32 v1, v1, v3
	v_and_b32_e32 v11, 48, v164
	v_cmp_eq_u32_e64 s[34:35], 0, v5
	v_lshrrev_b32_e32 v153, 8, v4
	v_lshl_add_u64 v[4:5], s[80:81], 0, v[112:113]
	s_mov_b64 s[38:39], 0xc000000
	s_add_u32 s74, s80, 0x16000000
	v_add_u32_e32 v1, 0xffffffbc, v1
	v_add_u32_e32 v148, 0, v11
	v_mul_u32_u24_e32 v149, 0x90, v146
	v_cmp_eq_u32_e64 s[22:23], 0, v6
	v_cmp_gt_u32_e64 s[36:37], 16, v180
	v_lshl_add_u64 v[116:117], v[4:5], 0, s[38:39]
	s_addc_u32 s75, s81, 0
	v_mov_b32_e32 v115, v113
	v_and_b32_e32 v156, 0xfc, v1
	v_lshlrev_b32_e32 v112, 1, v0
	s_mov_b64 s[52:53], 0x20000
	s_mov_b64 s[60:61], 0x100
	v_lshlrev_b32_e32 v118, 1, v2
	s_mov_b64 s[62:63], 0x39000000
	s_mov_b32 s76, 0x500000
	v_add_u32_e32 v157, 0, v10
	s_branch .LBB0_474

.LBB0_489:
	s_add_i32 s68, s48, -3
	s_cmp_ge_u32 s68, s38
	s_cselect_b64 s[64:65], -1, 0
	s_cmp_lt_u32 s68, s39
	s_cselect_b64 s[94:95], -1, 0
	s_and_b64 s[64:65], s[64:65], s[94:95]
	s_andn2_b64 vcc, exec, s[64:65]
	s_cbranch_vccnz .LBB0_491
	v_add_u32_e32 v178, v150, v149
	v_add_u32_e32 v181, 0x2000, v178
	v_add_u32_e32 v218, 0x2800, v178
	v_add_u32_e32 v219, 0x3000, v178
	v_add_u32_e32 v178, v150, v151
	v_add_u32_e32 v119, v148, v149
	v_add_u32_e32 v136, s66, v152
	v_add_u32_sdwa v163, s66, v143 dst_sel:DWORD dst_unused:UNUSED_PAD src0_sel:DWORD src1_sel:BYTE_2
	v_add_u32_sdwa v165, s66, v143 dst_sel:DWORD dst_unused:UNUSED_PAD src0_sel:DWORD src1_sel:BYTE_3
	v_add_u32_e32 v220, 0x2000, v178
	v_add_u32_sdwa v179, s66, v141 dst_sel:DWORD dst_unused:UNUSED_PAD src0_sel:DWORD src1_sel:BYTE_1
	ds_read_b128 v[158:161], v119
	ds_read_b128 v[166:169], v119 offset:64
	ds_read_b128 v[170:173], v119 offset:2304
	ds_read_b128 v[174:177], v119 offset:2368
	v_add_u32_e32 v162, s66, v153
	ds_read2_b64 v[182:185], v181 offset0:128 offset1:132
	ds_read2_b64 v[186:189], v218 offset0:160 offset1:164
	ds_read2_b64 v[190:193], v219 offset0:192 offset1:196
	ds_read2_b64 v[194:197], v220 offset0:128 offset1:132
	ds_read_b128 v[198:201], v119 offset:1152
	ds_read_b128 v[202:205], v119 offset:1216
	ds_read_b128 v[206:209], v119 offset:3456
	ds_read_b128 v[210:213], v119 offset:3520
	v_add_u32_e32 v178, s66, v155
	v_add_u32_sdwa v214, s66, v142 dst_sel:DWORD dst_unused:UNUSED_PAD src0_sel:DWORD src1_sel:BYTE_2
	v_add_u32_sdwa v215, s66, v142 dst_sel:DWORD dst_unused:UNUSED_PAD src0_sel:DWORD src1_sel:BYTE_3
	ds_read_b32 v136, v136 offset:41856
	ds_read_b32 v216, v162 offset:41856
	ds_read_b32 v163, v163 offset:41856
	ds_read_b32 v165, v165 offset:41856
	ds_read_b32 v217, v178 offset:41856
	ds_read_b32 v179, v179 offset:41856
	ds_read_b32 v221, v214 offset:41856
	ds_read_b32 v222, v215 offset:41856
	s_nop 0
	s_waitcnt vmcnt(7) lgkmcnt(14)
	v_mfma_f32_16x16x32_bf16 v[158:161], v[158:161], v[80:83], 0
	s_waitcnt vmcnt(6)
	v_mfma_f32_16x16x32_bf16 v[158:161], v[166:169], v[84:87], v[158:161]
	v_mfma_f32_16x16x32_bf16 v[166:169], v[170:173], v[80:83], 0
	v_mfma_f32_16x16x32_bf16 v[166:169], v[174:177], v[84:87], v[166:169]
	s_nop 0
	s_nop 6
	v_cndmask_b32_e64 v158, v166, v158, s[20:21]
	s_waitcnt lgkmcnt(7)
	v_add_f32_e32 v136, v136, v158
	v_exp_f32_e32 v162, v136
	v_cndmask_b32_e64 v136, v159, v167, s[10:11]
	v_cndmask_b32_e64 v159, v160, v168, s[12:13]
	s_waitcnt lgkmcnt(5)
	v_add_f32_e32 v159, v163, v159
	v_add_f32_e32 v136, v216, v136
	v_exp_f32_e32 v214, v159
	v_cndmask_b32_e64 v159, v161, v169, s[14:15]
	v_exp_f32_e32 v178, v136
	s_waitcnt lgkmcnt(4)
	v_add_f32_e32 v159, v165, v159
	v_exp_f32_e32 v216, v159
	v_cndmask_b32_e64 v159, v214, 0, s[12:13]
	v_cndmask_b32_e64 v158, v178, 0, s[10:11]
	v_cndmask_b32_e64 v160, 0, v178, s[10:11]
	v_cndmask_b32_e64 v161, 0, v214, s[12:13]
	v_cndmask_b32_e64 v136, 0, v162, s[20:21]
	v_cndmask_b32_e64 v166, v162, 0, s[20:21]
	v_cndmask_b32_e64 v163, v216, 0, s[14:15]
	v_cndmask_b32_e64 v165, 0, v216, s[14:15]
	v_cvt_pk_bf16_f32 v158, v136, v158
	v_cvt_pk_bf16_f32 v159, v159, v163
	v_cvt_pk_bf16_f32 v160, v166, v160
	v_cvt_pk_bf16_f32 v161, v161, v165
	s_nop 0
	v_mfma_f32_16x16x32_bf16 v[60:63], v[182:185], v[158:161], v[60:63]
	v_mfma_f32_16x16x32_bf16 v[56:59], v[186:189], v[158:161], v[56:59]
	v_mfma_f32_16x16x32_bf16 v[52:55], v[190:193], v[158:161], v[52:55]
	v_mfma_f32_16x16x32_bf16 v[48:51], v[194:197], v[158:161], v[48:51]
	s_nop 0
	ds_read2_b64 v[158:161], v181 offset0:130 offset1:134
	ds_read2_b64 v[166:169], v218 offset0:162 offset1:166
	ds_read2_b64 v[170:173], v219 offset0:194 offset1:198
	ds_read2_b64 v[174:177], v220 offset0:130 offset1:134
	ds_read_b128 v[182:185], v119 offset:3456
	ds_read_b128 v[186:189], v119 offset:3520
	ds_read_b128 v[190:193], v119 offset:5760
	ds_read_b128 v[194:197], v119 offset:5824
	v_add_u32_e32 v136, s66, v156
	v_add_u32_sdwa v165, s66, v140 dst_sel:DWORD dst_unused:UNUSED_PAD src0_sel:DWORD src1_sel:BYTE_2
	v_add_u32_sdwa v163, s66, v139 dst_sel:DWORD dst_unused:UNUSED_PAD src0_sel:DWORD src1_sel:BYTE_1
	v_add_u32_sdwa v215, s66, v140 dst_sel:DWORD dst_unused:UNUSED_PAD src0_sel:DWORD src1_sel:BYTE_3
	ds_read_b32 v136, v136 offset:41856
	ds_read_b32 v223, v163 offset:41856
	ds_read_b32 v165, v165 offset:41856
	ds_read_b32 v224, v215 offset:41856
	s_nop 0
	s_waitcnt vmcnt(5)
	v_mfma_f32_16x16x32_bf16 v[198:201], v[198:201], v[88:91], 0
	s_waitcnt vmcnt(4)
	v_mfma_f32_16x16x32_bf16 v[198:201], v[202:205], v[92:95], v[198:201]
	v_mfma_f32_16x16x32_bf16 v[202:205], v[206:209], v[88:91], 0
	v_mfma_f32_16x16x32_bf16 v[202:205], v[210:213], v[92:95], v[202:205]
	s_nop 0
	s_nop 6
	v_cndmask_b32_e64 v163, v198, v202, s[16:17]
	s_waitcnt lgkmcnt(14)
	v_add_f32_e32 v163, v217, v163
	v_cndmask_b32_e64 v198, v199, v203, s[18:19]
	v_cndmask_b32_e64 v200, v200, v204, s[6:7]
	v_exp_f32_e32 v163, v163
	v_add_f32_e32 v179, v179, v198
	s_waitcnt lgkmcnt(13)
	v_add_f32_e32 v200, v221, v200
	v_exp_f32_e32 v179, v179
	v_exp_f32_e32 v215, v200
	v_cndmask_b32_e64 v200, v201, v205, s[8:9]
	s_waitcnt lgkmcnt(12)
	v_add_f32_e32 v200, v222, v200
	v_exp_f32_e32 v217, v200
	v_cndmask_b32_e64 v198, v163, 0, s[16:17]
	v_cndmask_b32_e64 v202, 0, v163, s[16:17]
	v_pk_add_f32 v[162:163], v[162:163], 0 op_sel_hi:[1,0]
	v_cndmask_b32_e64 v199, v179, 0, s[18:19]
	v_pk_add_f32 v[162:163], v[178:179], v[162:163]
	v_cndmask_b32_e64 v200, 0, v179, s[18:19]
	v_pk_add_f32 v[162:163], v[214:215], v[162:163]
	v_cndmask_b32_e64 v201, v215, 0, s[6:7]
	v_pk_add_f32 v[162:163], v[216:217], v[162:163]
	v_cndmask_b32_e64 v203, 0, v215, s[6:7]
	v_pk_add_f32 v[130:131], v[130:131], v[162:163]
	v_cndmask_b32_e64 v204, v217, 0, s[8:9]
	v_cndmask_b32_e64 v205, 0, v217, s[8:9]
	v_cvt_pk_bf16_f32 v198, v198, v199
	v_cvt_pk_bf16_f32 v199, v201, v204
	v_cvt_pk_bf16_f32 v200, v202, v200
	v_cvt_pk_bf16_f32 v201, v203, v205
	s_nop 0
	s_waitcnt lgkmcnt(11)
	v_mfma_f32_16x16x32_bf16 v[44:47], v[158:161], v[198:201], v[44:47]
	s_waitcnt lgkmcnt(10)
	v_mfma_f32_16x16x32_bf16 v[40:43], v[166:169], v[198:201], v[40:43]
	s_waitcnt lgkmcnt(9)
	v_mfma_f32_16x16x32_bf16 v[36:39], v[170:173], v[198:201], v[36:39]
	s_waitcnt lgkmcnt(8)
	v_mfma_f32_16x16x32_bf16 v[32:35], v[174:177], v[198:201], v[32:35]
	s_nop 0
	ds_read2_b64 v[158:161], v181 offset0:134 offset1:138
	ds_read2_b64 v[166:169], v218 offset0:166 offset1:170
	ds_read2_b64 v[170:173], v219 offset0:198 offset1:202
	ds_read2_b64 v[174:177], v220 offset0:134 offset1:138
	ds_read_b128 v[198:201], v119 offset:4608
	ds_read_b128 v[202:205], v119 offset:4672
	v_add_u32_e32 v119, v148, v151
	ds_read_b128 v[206:209], v119
	ds_read_b128 v[210:213], v119 offset:64
	v_add_u32_e32 v119, s66, v154
	v_add_u32_sdwa v162, s66, v144 dst_sel:DWORD dst_unused:UNUSED_PAD src0_sel:DWORD src1_sel:BYTE_1
	v_add_u32_sdwa v163, s66, v145 dst_sel:DWORD dst_unused:UNUSED_PAD src0_sel:DWORD src1_sel:BYTE_2
	v_add_u32_sdwa v178, s66, v145 dst_sel:DWORD dst_unused:UNUSED_PAD src0_sel:DWORD src1_sel:BYTE_3
	ds_read_b32 v119, v119 offset:41856
	ds_read_b32 v179, v162 offset:41856
	ds_read_b32 v214, v163 offset:41856
	ds_read_b32 v215, v178 offset:41856
	s_nop 0
	s_waitcnt vmcnt(3) lgkmcnt(14)
	v_mfma_f32_16x16x32_bf16 v[182:185], v[182:185], v[96:99], 0
	s_waitcnt vmcnt(2)
	v_mfma_f32_16x16x32_bf16 v[182:185], v[186:189], v[100:103], v[182:185]
	v_mfma_f32_16x16x32_bf16 v[186:189], v[190:193], v[96:99], 0
	v_mfma_f32_16x16x32_bf16 v[186:189], v[194:197], v[100:103], v[186:189]
	s_nop 0
	s_nop 6
	v_cndmask_b32_e64 v162, v186, v182, s[2:3]
	v_add_f32_e32 v136, v136, v162
	v_exp_f32_e32 v162, v136
	v_cndmask_b32_e64 v136, v187, v183, s[4:5]
	v_cndmask_b32_e64 v183, v184, v188, s[22:23]
	s_waitcnt lgkmcnt(13)
	v_add_f32_e32 v165, v165, v183
	v_exp_f32_e32 v190, v165
	v_cndmask_b32_e64 v165, v185, v189, s[24:25]
	v_add_f32_e32 v136, v223, v136
	s_waitcnt lgkmcnt(12)
	v_add_f32_e32 v165, v224, v165
	v_exp_f32_e32 v178, v136
	v_exp_f32_e32 v192, v165
	v_cndmask_b32_e64 v183, v190, 0, s[22:23]
	v_cndmask_b32_e64 v185, 0, v190, s[22:23]
	v_cndmask_b32_e64 v182, 0, v178, s[4:5]
	v_cndmask_b32_e64 v184, v192, 0, s[24:25]
	v_cndmask_b32_e64 v136, 0, v162, s[2:3]
	v_cndmask_b32_e64 v163, v162, 0, s[2:3]
	v_cndmask_b32_e64 v165, v178, 0, s[4:5]
	v_cndmask_b32_e64 v186, 0, v192, s[24:25]
	v_cvt_pk_bf16_f32 v182, v136, v182
	v_cvt_pk_bf16_f32 v183, v183, v184
	v_cvt_pk_bf16_f32 v184, v163, v165
	v_cvt_pk_bf16_f32 v185, v185, v186
	s_nop 0
	s_waitcnt lgkmcnt(11)
	v_mfma_f32_16x16x32_bf16 v[28:31], v[158:161], v[182:185], v[28:31]
	s_waitcnt lgkmcnt(10)
	v_mfma_f32_16x16x32_bf16 v[24:27], v[166:169], v[182:185], v[24:27]
	s_waitcnt lgkmcnt(9)
	v_mfma_f32_16x16x32_bf16 v[20:23], v[170:173], v[182:185], v[20:23]
	s_waitcnt lgkmcnt(8)
	v_mfma_f32_16x16x32_bf16 v[16:19], v[174:177], v[182:185], v[16:19]
	s_nop 0
	ds_read2_b64 v[158:161], v220 offset0:136 offset1:140
	ds_read2_b64 v[166:169], v219 offset0:200 offset1:204
	ds_read2_b64 v[170:173], v218 offset0:168 offset1:172
	ds_read2_b64 v[174:177], v181 offset0:136 offset1:140
	s_nop 0
	s_waitcnt vmcnt(1) lgkmcnt(11)
	v_mfma_f32_16x16x32_bf16 v[182:185], v[198:201], v[104:107], 0
	s_waitcnt lgkmcnt(9)
	v_mfma_f32_16x16x32_bf16 v[186:189], v[206:209], v[104:107], 0
	s_waitcnt vmcnt(0)
	v_mfma_f32_16x16x32_bf16 v[182:185], v[202:205], v[108:111], v[182:185]
	s_waitcnt lgkmcnt(8)
	v_mfma_f32_16x16x32_bf16 v[186:189], v[210:213], v[108:111], v[186:189]
	s_nop 0
	s_nop 6
	v_cndmask_b32_e64 v136, v182, v186, s[26:27]
	s_waitcnt lgkmcnt(7)
	v_add_f32_e32 v119, v119, v136
	v_exp_f32_e32 v163, v119
	v_cndmask_b32_e64 v119, v183, v187, s[28:29]
	v_cndmask_b32_e64 v181, v184, v188, s[30:31]
	s_waitcnt lgkmcnt(6)
	v_add_f32_e32 v119, v179, v119
	s_waitcnt lgkmcnt(5)
	v_add_f32_e32 v181, v214, v181
	v_exp_f32_e32 v179, v119
	v_exp_f32_e32 v191, v181
	v_cndmask_b32_e64 v181, v185, v189, s[34:35]
	s_waitcnt lgkmcnt(4)
	v_add_f32_e32 v181, v215, v181
	v_exp_f32_e32 v193, v181
	v_cndmask_b32_e64 v119, v163, 0, s[26:27]
	v_cndmask_b32_e64 v136, 0, v163, s[26:27]
	v_pk_add_f32 v[162:163], v[162:163], 0 op_sel_hi:[1,0]
	v_cndmask_b32_e64 v183, v191, 0, s[30:31]
	v_pk_add_f32 v[162:163], v[178:179], v[162:163]
	v_cndmask_b32_e64 v185, 0, v191, s[30:31]
	v_pk_add_f32 v[162:163], v[190:191], v[162:163]
	v_cndmask_b32_e64 v184, v193, 0, s[34:35]
	v_pk_add_f32 v[162:163], v[192:193], v[162:163]
	v_cndmask_b32_e64 v165, v179, 0, s[28:29]
	v_pk_add_f32 v[124:125], v[124:125], v[162:163]
	v_cndmask_b32_e64 v181, 0, v179, s[28:29]
	v_cndmask_b32_e64 v186, 0, v193, s[34:35]
	v_cvt_pk_bf16_f32 v182, v119, v165
	v_cvt_pk_bf16_f32 v183, v183, v184
	v_cvt_pk_bf16_f32 v184, v136, v181
	v_cvt_pk_bf16_f32 v185, v185, v186
	s_nop 0
	s_waitcnt lgkmcnt(0)
	v_mfma_f32_16x16x32_bf16 v[12:15], v[174:177], v[182:185], v[12:15]
	v_mfma_f32_16x16x32_bf16 v[8:11], v[170:173], v[182:185], v[8:11]
	v_mfma_f32_16x16x32_bf16 v[4:7], v[166:169], v[182:185], v[4:7]
	v_mfma_f32_16x16x32_bf16 v[0:3], v[158:161], v[182:185], v[0:3]
	s_nop 0

.LBB0_496:
	s_add_i32 s64, s48, -2
	s_cmp_ge_u32 s64, s38
	s_cselect_b64 s[68:69], -1, 0
	s_cmp_lt_u32 s64, s39
	s_cselect_b64 s[94:95], -1, 0
	s_and_b64 s[68:69], s[68:69], s[94:95]
	s_andn2_b64 vcc, exec, s[68:69]
	s_cbranch_vccnz .LBB0_498
	v_add_u32_e32 v178, v150, v149
	v_add_u32_e32 v181, 0x6800, v178
	v_add_u32_e32 v218, 0x7000, v178
	v_add_u32_e32 v219, 0x7800, v178
	v_add_u32_e32 v178, v150, v151
	v_add_u32_e32 v119, v148, v149
	v_add_u32_e32 v136, s66, v152
	v_add_u32_sdwa v163, s66, v143 dst_sel:DWORD dst_unused:UNUSED_PAD src0_sel:DWORD src1_sel:BYTE_2
	v_add_u32_sdwa v165, s66, v143 dst_sel:DWORD dst_unused:UNUSED_PAD src0_sel:DWORD src1_sel:BYTE_3
	v_add_u32_e32 v220, 0x6800, v178
	v_add_u32_sdwa v179, s66, v141 dst_sel:DWORD dst_unused:UNUSED_PAD src0_sel:DWORD src1_sel:BYTE_1
	ds_read_b128 v[158:161], v119 offset:18432
	ds_read_b128 v[166:169], v119 offset:18496
	ds_read_b128 v[170:173], v119 offset:20736
	ds_read_b128 v[174:177], v119 offset:20800
	v_add_u32_e32 v162, s66, v153
	ds_read2_b64 v[182:185], v181 offset0:128 offset1:132
	ds_read2_b64 v[186:189], v218 offset0:160 offset1:164
	ds_read2_b64 v[190:193], v219 offset0:192 offset1:196
	ds_read2_b64 v[194:197], v220 offset0:128 offset1:132
	ds_read_b128 v[198:201], v119 offset:19584
	ds_read_b128 v[202:205], v119 offset:19648
	ds_read_b128 v[206:209], v119 offset:21888
	ds_read_b128 v[210:213], v119 offset:21952
	v_add_u32_e32 v178, s66, v155
	v_add_u32_sdwa v214, s66, v142 dst_sel:DWORD dst_unused:UNUSED_PAD src0_sel:DWORD src1_sel:BYTE_2
	v_add_u32_sdwa v215, s66, v142 dst_sel:DWORD dst_unused:UNUSED_PAD src0_sel:DWORD src1_sel:BYTE_3
	ds_read_b32 v136, v136 offset:41984
	ds_read_b32 v216, v162 offset:41984
	ds_read_b32 v163, v163 offset:41984
	ds_read_b32 v165, v165 offset:41984
	ds_read_b32 v217, v178 offset:41984
	ds_read_b32 v179, v179 offset:41984
	ds_read_b32 v221, v214 offset:41984
	ds_read_b32 v222, v215 offset:41984
	s_nop 0
	s_waitcnt vmcnt(7) lgkmcnt(14)
	v_mfma_f32_16x16x32_bf16 v[158:161], v[158:161], v[80:83], 0
	s_waitcnt vmcnt(6)
	v_mfma_f32_16x16x32_bf16 v[158:161], v[166:169], v[84:87], v[158:161]
	v_mfma_f32_16x16x32_bf16 v[166:169], v[170:173], v[80:83], 0
	v_mfma_f32_16x16x32_bf16 v[166:169], v[174:177], v[84:87], v[166:169]
	s_nop 0
	s_nop 6
	v_cndmask_b32_e64 v158, v166, v158, s[20:21]
	s_waitcnt lgkmcnt(7)
	v_add_f32_e32 v136, v136, v158
	v_exp_f32_e32 v162, v136
	v_cndmask_b32_e64 v136, v159, v167, s[10:11]
	v_cndmask_b32_e64 v159, v160, v168, s[12:13]
	s_waitcnt lgkmcnt(5)
	v_add_f32_e32 v159, v163, v159
	v_add_f32_e32 v136, v216, v136
	v_exp_f32_e32 v214, v159
	v_cndmask_b32_e64 v159, v161, v169, s[14:15]
	v_exp_f32_e32 v178, v136
	s_waitcnt lgkmcnt(4)
	v_add_f32_e32 v159, v165, v159
	v_exp_f32_e32 v216, v159
	v_cndmask_b32_e64 v159, v214, 0, s[12:13]
	v_cndmask_b32_e64 v158, v178, 0, s[10:11]
	v_cndmask_b32_e64 v160, 0, v178, s[10:11]
	v_cndmask_b32_e64 v161, 0, v214, s[12:13]
	v_cndmask_b32_e64 v136, 0, v162, s[20:21]
	v_cndmask_b32_e64 v166, v162, 0, s[20:21]
	v_cndmask_b32_e64 v163, v216, 0, s[14:15]
	v_cndmask_b32_e64 v165, 0, v216, s[14:15]
	v_cvt_pk_bf16_f32 v158, v136, v158
	v_cvt_pk_bf16_f32 v159, v159, v163
	v_cvt_pk_bf16_f32 v160, v166, v160
	v_cvt_pk_bf16_f32 v161, v161, v165
	s_nop 0
	v_mfma_f32_16x16x32_bf16 v[60:63], v[182:185], v[158:161], v[60:63]
	v_mfma_f32_16x16x32_bf16 v[56:59], v[186:189], v[158:161], v[56:59]
	v_mfma_f32_16x16x32_bf16 v[52:55], v[190:193], v[158:161], v[52:55]
	v_mfma_f32_16x16x32_bf16 v[48:51], v[194:197], v[158:161], v[48:51]
	s_nop 0
	ds_read2_b64 v[158:161], v181 offset0:130 offset1:134
	ds_read2_b64 v[166:169], v218 offset0:162 offset1:166
	ds_read2_b64 v[170:173], v219 offset0:194 offset1:198
	ds_read2_b64 v[174:177], v220 offset0:130 offset1:134
	ds_read_b128 v[182:185], v119 offset:21888
	ds_read_b128 v[186:189], v119 offset:21952
	ds_read_b128 v[190:193], v119 offset:24192
	ds_read_b128 v[194:197], v119 offset:24256
	v_add_u32_e32 v136, s66, v156
	v_add_u32_sdwa v165, s66, v140 dst_sel:DWORD dst_unused:UNUSED_PAD src0_sel:DWORD src1_sel:BYTE_2
	v_add_u32_sdwa v163, s66, v139 dst_sel:DWORD dst_unused:UNUSED_PAD src0_sel:DWORD src1_sel:BYTE_1
	v_add_u32_sdwa v215, s66, v140 dst_sel:DWORD dst_unused:UNUSED_PAD src0_sel:DWORD src1_sel:BYTE_3
	ds_read_b32 v136, v136 offset:41984
	ds_read_b32 v223, v163 offset:41984
	ds_read_b32 v165, v165 offset:41984
	ds_read_b32 v224, v215 offset:41984
	s_nop 0
	s_waitcnt vmcnt(5)
	v_mfma_f32_16x16x32_bf16 v[198:201], v[198:201], v[88:91], 0
	s_waitcnt vmcnt(4)
	v_mfma_f32_16x16x32_bf16 v[198:201], v[202:205], v[92:95], v[198:201]
	v_mfma_f32_16x16x32_bf16 v[202:205], v[206:209], v[88:91], 0
	v_mfma_f32_16x16x32_bf16 v[202:205], v[210:213], v[92:95], v[202:205]
	s_nop 0
	s_nop 6
	v_cndmask_b32_e64 v163, v198, v202, s[16:17]
	s_waitcnt lgkmcnt(14)
	v_add_f32_e32 v163, v217, v163
	v_cndmask_b32_e64 v198, v199, v203, s[18:19]
	v_cndmask_b32_e64 v200, v200, v204, s[6:7]
	v_exp_f32_e32 v163, v163
	v_add_f32_e32 v179, v179, v198
	s_waitcnt lgkmcnt(13)
	v_add_f32_e32 v200, v221, v200
	v_exp_f32_e32 v179, v179
	v_exp_f32_e32 v215, v200
	v_cndmask_b32_e64 v200, v201, v205, s[8:9]
	s_waitcnt lgkmcnt(12)
	v_add_f32_e32 v200, v222, v200
	v_exp_f32_e32 v217, v200
	v_cndmask_b32_e64 v198, v163, 0, s[16:17]
	v_cndmask_b32_e64 v202, 0, v163, s[16:17]
	v_pk_add_f32 v[162:163], v[162:163], 0 op_sel_hi:[1,0]
	v_cndmask_b32_e64 v199, v179, 0, s[18:19]
	v_pk_add_f32 v[162:163], v[178:179], v[162:163]
	v_cndmask_b32_e64 v200, 0, v179, s[18:19]
	v_pk_add_f32 v[162:163], v[214:215], v[162:163]
	v_cndmask_b32_e64 v201, v215, 0, s[6:7]
	v_pk_add_f32 v[162:163], v[216:217], v[162:163]
	v_cndmask_b32_e64 v203, 0, v215, s[6:7]
	v_pk_add_f32 v[130:131], v[130:131], v[162:163]
	v_cndmask_b32_e64 v204, v217, 0, s[8:9]
	v_cndmask_b32_e64 v205, 0, v217, s[8:9]
	v_cvt_pk_bf16_f32 v198, v198, v199
	v_cvt_pk_bf16_f32 v199, v201, v204
	v_cvt_pk_bf16_f32 v200, v202, v200
	v_cvt_pk_bf16_f32 v201, v203, v205
	s_nop 0
	s_waitcnt lgkmcnt(11)
	v_mfma_f32_16x16x32_bf16 v[44:47], v[158:161], v[198:201], v[44:47]
	s_waitcnt lgkmcnt(10)
	v_mfma_f32_16x16x32_bf16 v[40:43], v[166:169], v[198:201], v[40:43]
	s_waitcnt lgkmcnt(9)
	v_mfma_f32_16x16x32_bf16 v[36:39], v[170:173], v[198:201], v[36:39]
	s_waitcnt lgkmcnt(8)
	v_mfma_f32_16x16x32_bf16 v[32:35], v[174:177], v[198:201], v[32:35]
	s_nop 0
	ds_read2_b64 v[158:161], v181 offset0:134 offset1:138
	ds_read2_b64 v[166:169], v218 offset0:166 offset1:170
	ds_read2_b64 v[170:173], v219 offset0:198 offset1:202
	ds_read2_b64 v[174:177], v220 offset0:134 offset1:138
	ds_read_b128 v[198:201], v119 offset:23040
	ds_read_b128 v[202:205], v119 offset:23104
	v_add_u32_e32 v119, v148, v151
	ds_read_b128 v[206:209], v119 offset:18432
	ds_read_b128 v[210:213], v119 offset:18496
	v_add_u32_e32 v119, s66, v154
	v_add_u32_sdwa v162, s66, v144 dst_sel:DWORD dst_unused:UNUSED_PAD src0_sel:DWORD src1_sel:BYTE_1
	v_add_u32_sdwa v163, s66, v145 dst_sel:DWORD dst_unused:UNUSED_PAD src0_sel:DWORD src1_sel:BYTE_2
	v_add_u32_sdwa v178, s66, v145 dst_sel:DWORD dst_unused:UNUSED_PAD src0_sel:DWORD src1_sel:BYTE_3
	ds_read_b32 v119, v119 offset:41984
	ds_read_b32 v179, v162 offset:41984
	ds_read_b32 v214, v163 offset:41984
	ds_read_b32 v215, v178 offset:41984
	s_nop 0
	s_waitcnt vmcnt(3) lgkmcnt(14)
	v_mfma_f32_16x16x32_bf16 v[182:185], v[182:185], v[96:99], 0
	s_waitcnt vmcnt(2)
	v_mfma_f32_16x16x32_bf16 v[182:185], v[186:189], v[100:103], v[182:185]
	v_mfma_f32_16x16x32_bf16 v[186:189], v[190:193], v[96:99], 0
	v_mfma_f32_16x16x32_bf16 v[186:189], v[194:197], v[100:103], v[186:189]
	s_nop 0
	s_nop 6
	v_cndmask_b32_e64 v162, v186, v182, s[2:3]
	v_add_f32_e32 v136, v136, v162
	v_exp_f32_e32 v162, v136
	v_cndmask_b32_e64 v136, v187, v183, s[4:5]
	v_cndmask_b32_e64 v183, v184, v188, s[22:23]
	s_waitcnt lgkmcnt(13)
	v_add_f32_e32 v165, v165, v183
	v_exp_f32_e32 v190, v165
	v_cndmask_b32_e64 v165, v185, v189, s[24:25]
	v_add_f32_e32 v136, v223, v136
	s_waitcnt lgkmcnt(12)
	v_add_f32_e32 v165, v224, v165
	v_exp_f32_e32 v178, v136
	v_exp_f32_e32 v192, v165
	v_cndmask_b32_e64 v183, v190, 0, s[22:23]
	v_cndmask_b32_e64 v185, 0, v190, s[22:23]
	v_cndmask_b32_e64 v182, 0, v178, s[4:5]
	v_cndmask_b32_e64 v184, v192, 0, s[24:25]
	v_cndmask_b32_e64 v136, 0, v162, s[2:3]
	v_cndmask_b32_e64 v163, v162, 0, s[2:3]
	v_cndmask_b32_e64 v165, v178, 0, s[4:5]
	v_cndmask_b32_e64 v186, 0, v192, s[24:25]
	v_cvt_pk_bf16_f32 v182, v136, v182
	v_cvt_pk_bf16_f32 v183, v183, v184
	v_cvt_pk_bf16_f32 v184, v163, v165
	v_cvt_pk_bf16_f32 v185, v185, v186
	s_nop 0
	s_waitcnt lgkmcnt(11)
	v_mfma_f32_16x16x32_bf16 v[28:31], v[158:161], v[182:185], v[28:31]
	s_waitcnt lgkmcnt(10)
	v_mfma_f32_16x16x32_bf16 v[24:27], v[166:169], v[182:185], v[24:27]
	s_waitcnt lgkmcnt(9)
	v_mfma_f32_16x16x32_bf16 v[20:23], v[170:173], v[182:185], v[20:23]
	s_waitcnt lgkmcnt(8)
	v_mfma_f32_16x16x32_bf16 v[16:19], v[174:177], v[182:185], v[16:19]
	s_nop 0
	ds_read2_b64 v[158:161], v220 offset0:136 offset1:140
	ds_read2_b64 v[166:169], v219 offset0:200 offset1:204
	ds_read2_b64 v[170:173], v218 offset0:168 offset1:172
	ds_read2_b64 v[174:177], v181 offset0:136 offset1:140
	s_nop 0
	s_waitcnt vmcnt(1) lgkmcnt(11)
	v_mfma_f32_16x16x32_bf16 v[182:185], v[198:201], v[104:107], 0
	s_waitcnt lgkmcnt(9)
	v_mfma_f32_16x16x32_bf16 v[186:189], v[206:209], v[104:107], 0
	s_waitcnt vmcnt(0)
	v_mfma_f32_16x16x32_bf16 v[182:185], v[202:205], v[108:111], v[182:185]
	s_waitcnt lgkmcnt(8)
	v_mfma_f32_16x16x32_bf16 v[186:189], v[210:213], v[108:111], v[186:189]
	s_nop 0
	s_nop 6
	v_cndmask_b32_e64 v136, v182, v186, s[26:27]
	s_waitcnt lgkmcnt(7)
	v_add_f32_e32 v119, v119, v136
	v_exp_f32_e32 v163, v119
	v_cndmask_b32_e64 v119, v183, v187, s[28:29]
	v_cndmask_b32_e64 v181, v184, v188, s[30:31]
	s_waitcnt lgkmcnt(6)
	v_add_f32_e32 v119, v179, v119
	s_waitcnt lgkmcnt(5)
	v_add_f32_e32 v181, v214, v181
	v_exp_f32_e32 v179, v119
	v_exp_f32_e32 v191, v181
	v_cndmask_b32_e64 v181, v185, v189, s[34:35]
	s_waitcnt lgkmcnt(4)
	v_add_f32_e32 v181, v215, v181
	v_exp_f32_e32 v193, v181
	v_cndmask_b32_e64 v119, v163, 0, s[26:27]
	v_cndmask_b32_e64 v136, 0, v163, s[26:27]
	v_pk_add_f32 v[162:163], v[162:163], 0 op_sel_hi:[1,0]
	v_cndmask_b32_e64 v183, v191, 0, s[30:31]
	v_pk_add_f32 v[162:163], v[178:179], v[162:163]
	v_cndmask_b32_e64 v185, 0, v191, s[30:31]
	v_pk_add_f32 v[162:163], v[190:191], v[162:163]
	v_cndmask_b32_e64 v184, v193, 0, s[34:35]
	v_pk_add_f32 v[162:163], v[192:193], v[162:163]
	v_cndmask_b32_e64 v165, v179, 0, s[28:29]
	v_pk_add_f32 v[124:125], v[124:125], v[162:163]
	v_cndmask_b32_e64 v181, 0, v179, s[28:29]
	v_cndmask_b32_e64 v186, 0, v193, s[34:35]
	v_cvt_pk_bf16_f32 v182, v119, v165
	v_cvt_pk_bf16_f32 v183, v183, v184
	v_cvt_pk_bf16_f32 v184, v136, v181
	v_cvt_pk_bf16_f32 v185, v185, v186
	s_nop 0
	s_waitcnt lgkmcnt(0)
	v_mfma_f32_16x16x32_bf16 v[12:15], v[174:177], v[182:185], v[12:15]
	v_mfma_f32_16x16x32_bf16 v[8:11], v[170:173], v[182:185], v[8:11]
	v_mfma_f32_16x16x32_bf16 v[4:7], v[166:169], v[182:185], v[4:7]
	v_mfma_f32_16x16x32_bf16 v[0:3], v[158:161], v[182:185], v[0:3]
	s_nop 0

.LBB0_563:
	s_cmp_lt_i32 s82, 5
	s_cselect_b64 s[2:3], -1, 0
	s_and_b64 s[44:45], s[2:3], s[0:1]
	s_andn2_b64 vcc, exec, s[44:45]
	s_cbranch_vccnz .LBB0_710
	s_and_b32 s0, s33, 1
	s_cmp_eq_u32 s0, 0
	s_cselect_b64 s[48:49], -1, 0
	s_cmp_eq_u32 s0, 1
	s_cselect_b64 s[0:1], -1, 0
	s_movk_i32 s50, 0x80
	s_and_b64 vcc, exec, s[0:1]
	s_mul_i32 s97, s92, 0x1d1
	s_cbranch_vccz .LBB0_571
	v_lshrrev_b32_e32 v0, 5, v180
	v_and_b32_e32 v7, 31, v180
	v_mul_u32_u24_e32 v0, 31, v0
	v_add3_u32 v0, s97, v0, v7
	v_lshlrev_b32_e32 v0, 2, v0
	v_cmp_ne_u32_e32 vcc, 31, v7
	v_lshlrev_b32_e32 v16, 2, v180
	v_mov_b32_e32 v20, 0
	v_mov_b32_e32 v21, 0
	v_mov_b32_e32 v22, 0
	v_mov_b32_e32 v23, 0
	v_mov_b32_e32 v24, 0
	v_mov_b32_e32 v25, 0
	v_mov_b32_e32 v26, 0
	v_mov_b32_e32 v27, 0
	s_waitcnt lgkmcnt(0)
	global_load_dword v2, v16, s[40:41]
	global_load_dword v3, v16, s[42:43]
	s_mov_b64 s[2:3], exec
	v_cmp_gt_u32_e64 s[0:1], 32, v180
	s_and_b64 exec, exec, vcc
	global_load_dword v20, v0, s[46:47]
	global_load_dword v21, v0, s[46:47] offset:248
	global_load_dword v22, v0, s[46:47] offset:496
	global_load_dword v23, v0, s[46:47] offset:744
	global_load_dword v24, v0, s[46:47] offset:992
	global_load_dword v25, v0, s[46:47] offset:1240
	global_load_dword v26, v0, s[46:47] offset:1488
	s_and_b64 exec, exec, s[0:1]
	global_load_dword v27, v0, s[46:47] offset:1736
	s_mov_b64 exec, s[2:3]
	v_xor_b32_e32 v8, 1, v180
	v_lshlrev_b32_e32 v8, 2, v8
	v_xor_b32_e32 v9, 2, v180
	v_lshlrev_b32_e32 v9, 2, v9
	v_xor_b32_e32 v10, 4, v180
	v_lshlrev_b32_e32 v10, 2, v10
	v_xor_b32_e32 v11, 8, v180
	v_lshlrev_b32_e32 v11, 2, v11
	v_xor_b32_e32 v138, 16, v180
	v_lshlrev_b32_e32 v138, 2, v138
	v_xor_b32_e32 v139, 32, v180
	v_lshlrev_b32_e32 v139, 2, v139
	s_mul_i32 s5, s92, 0x780
	v_add_u32_e32 v16, s5, v16
	v_add_u32_e32 v16, 0xa000, v16
	s_waitcnt vmcnt(8)
	v_max_f32_e64 v5, |v2|, |v2|
	v_max_f32_e64 v6, |v3|, |v3|
	s_waitcnt vmcnt(0)
	v_max_f32_e64 v1, |v20|, |v21|
	v_max_f32_e64 v4, |v22|, |v23|
	v_max_f32_e64 v12, |v24|, |v25|
	v_max_f32_e64 v13, |v26|, |v27|
	v_max_f32_e32 v1, v1, v4
	v_max_f32_e32 v12, v12, v13
	v_max_f32_e32 v1, v1, v12
	ds_bpermute_b32 v12, v8, v1
	ds_bpermute_b32 v13, v8, v5
	ds_bpermute_b32 v14, v8, v6
	s_waitcnt lgkmcnt(0)
	v_max_f32_e32 v1, v1, v12
	v_max_f32_e32 v5, v5, v13
	v_max_f32_e32 v6, v6, v14
	ds_bpermute_b32 v12, v9, v1
	ds_bpermute_b32 v13, v9, v5
	ds_bpermute_b32 v14, v9, v6
	s_waitcnt lgkmcnt(0)
	v_max_f32_e32 v1, v1, v12
	v_max_f32_e32 v5, v5, v13
	v_max_f32_e32 v6, v6, v14
	ds_bpermute_b32 v12, v10, v1
	ds_bpermute_b32 v13, v10, v5
	ds_bpermute_b32 v14, v10, v6
	s_waitcnt lgkmcnt(0)
	v_max_f32_e32 v1, v1, v12
	v_max_f32_e32 v5, v5, v13
	v_max_f32_e32 v6, v6, v14
	ds_bpermute_b32 v12, v11, v1
	ds_bpermute_b32 v13, v11, v5
	ds_bpermute_b32 v14, v11, v6
	s_waitcnt lgkmcnt(0)
	v_max_f32_e32 v1, v1, v12
	v_max_f32_e32 v5, v5, v13
	v_max_f32_e32 v6, v6, v14
	ds_bpermute_b32 v12, v138, v1
	ds_bpermute_b32 v13, v138, v5
	ds_bpermute_b32 v14, v138, v6
	s_waitcnt lgkmcnt(0)
	v_max_f32_e32 v1, v1, v12
	v_max_f32_e32 v5, v5, v13
	v_max_f32_e32 v6, v6, v14
	ds_bpermute_b32 v12, v139, v1
	ds_bpermute_b32 v13, v139, v5
	ds_bpermute_b32 v14, v139, v6
	s_waitcnt lgkmcnt(0)
	v_max_f32_e32 v1, v1, v12
	v_max_f32_e32 v5, v5, v13
	v_max_f32_e32 v6, v6, v14
	v_mul_f32_e32 v5, 0x41000000, v5
	v_fmac_f32_e32 v1, v6, v5
	v_mov_b32_e32 v15, 0xf149f2ca
	v_sub_f32_e32 v12, v20, v1
	v_mul_f32_e32 v12, 0x3fb8aa3b, v12
	v_cndmask_b32_e32 v12, v15, v12, vcc
	ds_write_b32 v16, v12
	v_sub_f32_e32 v12, v21, v1
	v_mul_f32_e32 v12, 0x3fb8aa3b, v12
	v_cndmask_b32_e32 v12, v15, v12, vcc
	ds_write_b32 v16, v12 offset:256
	v_sub_f32_e32 v12, v22, v1
	v_mul_f32_e32 v12, 0x3fb8aa3b, v12
	v_cndmask_b32_e32 v12, v15, v12, vcc
	ds_write_b32 v16, v12 offset:512
	v_sub_f32_e32 v12, v23, v1
	v_mul_f32_e32 v12, 0x3fb8aa3b, v12
	v_cndmask_b32_e32 v12, v15, v12, vcc
	ds_write_b32 v16, v12 offset:768
	v_sub_f32_e32 v12, v24, v1
	v_mul_f32_e32 v12, 0x3fb8aa3b, v12
	v_cndmask_b32_e32 v12, v15, v12, vcc
	ds_write_b32 v16, v12 offset:1024
	v_sub_f32_e32 v12, v25, v1
	v_mul_f32_e32 v12, 0x3fb8aa3b, v12
	v_cndmask_b32_e32 v12, v15, v12, vcc
	ds_write_b32 v16, v12 offset:1280
	v_sub_f32_e32 v12, v26, v1
	v_mul_f32_e32 v12, 0x3fb8aa3b, v12
	v_cndmask_b32_e32 v12, v15, v12, vcc
	ds_write_b32 v16, v12 offset:1536
	v_sub_f32_e32 v12, v27, v1
	v_mul_f32_e32 v12, 0x3fb8aa3b, v12
	v_cndmask_b32_e32 v12, v15, v12, vcc
	s_and_b64 exec, exec, s[0:1]
	ds_write_b32 v16, v12 offset:1792
	s_mov_b64 exec, s[2:3]
	s_cmp_ge_u32 s92, 4
	s_cbranch_scc0 .Lprio_a2
	s_setprio 1

.LBB0_590:
	s_add_i32 s70, s52, -3
	s_cmp_ge_u32 s70, s38
	s_cselect_b64 s[66:67], -1, 0
	s_cmp_lt_u32 s70, s39
	s_cselect_b64 s[72:73], -1, 0
	s_and_b64 s[66:67], s[66:67], s[72:73]
	s_andn2_b64 vcc, exec, s[66:67]
	s_cbranch_vccnz .LBB0_592
	v_add_u32_e32 v178, v150, v149
	v_add_u32_e32 v181, 0x2000, v178
	v_add_u32_e32 v218, 0x2800, v178
	v_add_u32_e32 v219, 0x3000, v178
	v_add_u32_e32 v178, v150, v151
	v_add_u32_e32 v119, v148, v149
	v_add_u32_e32 v136, s68, v152
	v_add_u32_sdwa v163, s68, v144 dst_sel:DWORD dst_unused:UNUSED_PAD src0_sel:DWORD src1_sel:BYTE_2
	v_add_u32_sdwa v165, s68, v144 dst_sel:DWORD dst_unused:UNUSED_PAD src0_sel:DWORD src1_sel:BYTE_3
	v_add_u32_e32 v220, 0x2000, v178
	v_add_u32_sdwa v179, s68, v142 dst_sel:DWORD dst_unused:UNUSED_PAD src0_sel:DWORD src1_sel:BYTE_1
	ds_read_b128 v[158:161], v119
	ds_read_b128 v[166:169], v119 offset:64
	ds_read_b128 v[170:173], v119 offset:2304
	ds_read_b128 v[174:177], v119 offset:2368
	v_add_u32_e32 v162, s68, v153
	ds_read2_b64 v[182:185], v181 offset0:128 offset1:132
	ds_read2_b64 v[186:189], v218 offset0:160 offset1:164
	ds_read2_b64 v[190:193], v219 offset0:192 offset1:196
	ds_read2_b64 v[194:197], v220 offset0:128 offset1:132
	ds_read_b128 v[198:201], v119 offset:1152
	ds_read_b128 v[202:205], v119 offset:1216
	ds_read_b128 v[206:209], v119 offset:3456
	ds_read_b128 v[210:213], v119 offset:3520
	v_add_u32_e32 v178, s68, v155
	v_add_u32_sdwa v214, s68, v143 dst_sel:DWORD dst_unused:UNUSED_PAD src0_sel:DWORD src1_sel:BYTE_2
	v_add_u32_sdwa v215, s68, v143 dst_sel:DWORD dst_unused:UNUSED_PAD src0_sel:DWORD src1_sel:BYTE_3
	ds_read_b32 v136, v136 offset:41856
	ds_read_b32 v216, v162 offset:41856
	ds_read_b32 v163, v163 offset:41856
	ds_read_b32 v165, v165 offset:41856
	ds_read_b32 v217, v178 offset:41856
	ds_read_b32 v179, v179 offset:41856
	ds_read_b32 v221, v214 offset:41856
	ds_read_b32 v222, v215 offset:41856
	s_nop 0
	s_waitcnt vmcnt(7) lgkmcnt(14)
	v_mfma_f32_16x16x32_bf16 v[158:161], v[158:161], v[80:83], 0
	s_waitcnt vmcnt(6)
	v_mfma_f32_16x16x32_bf16 v[158:161], v[166:169], v[84:87], v[158:161]
	v_mfma_f32_16x16x32_bf16 v[166:169], v[170:173], v[80:83], 0
	v_mfma_f32_16x16x32_bf16 v[166:169], v[174:177], v[84:87], v[166:169]
	s_nop 0
	s_nop 6
	v_cndmask_b32_e64 v158, v166, v158, s[20:21]
	s_waitcnt lgkmcnt(7)
	v_add_f32_e32 v136, v136, v158
	v_exp_f32_e32 v162, v136
	v_cndmask_b32_e64 v136, v159, v167, s[10:11]
	v_cndmask_b32_e64 v159, v160, v168, s[12:13]
	s_waitcnt lgkmcnt(5)
	v_add_f32_e32 v159, v163, v159
	v_add_f32_e32 v136, v216, v136
	v_exp_f32_e32 v214, v159
	v_cndmask_b32_e64 v159, v161, v169, s[14:15]
	v_exp_f32_e32 v178, v136
	s_waitcnt lgkmcnt(4)
	v_add_f32_e32 v159, v165, v159
	v_exp_f32_e32 v216, v159
	v_cndmask_b32_e64 v159, v214, 0, s[12:13]
	v_cndmask_b32_e64 v158, v178, 0, s[10:11]
	v_cndmask_b32_e64 v160, 0, v178, s[10:11]
	v_cndmask_b32_e64 v161, 0, v214, s[12:13]
	v_cndmask_b32_e64 v136, 0, v162, s[20:21]
	v_cndmask_b32_e64 v166, v162, 0, s[20:21]
	v_cndmask_b32_e64 v163, v216, 0, s[14:15]
	v_cndmask_b32_e64 v165, 0, v216, s[14:15]
	v_cvt_pk_bf16_f32 v158, v136, v158
	v_cvt_pk_bf16_f32 v159, v159, v163
	v_cvt_pk_bf16_f32 v160, v166, v160
	v_cvt_pk_bf16_f32 v161, v161, v165
	s_nop 0
	v_mfma_f32_16x16x32_bf16 v[60:63], v[182:185], v[158:161], v[60:63]
	v_mfma_f32_16x16x32_bf16 v[56:59], v[186:189], v[158:161], v[56:59]
	v_mfma_f32_16x16x32_bf16 v[52:55], v[190:193], v[158:161], v[52:55]
	v_mfma_f32_16x16x32_bf16 v[48:51], v[194:197], v[158:161], v[48:51]
	s_nop 0
	ds_read2_b64 v[158:161], v181 offset0:130 offset1:134
	ds_read2_b64 v[166:169], v218 offset0:162 offset1:166
	ds_read2_b64 v[170:173], v219 offset0:194 offset1:198
	ds_read2_b64 v[174:177], v220 offset0:130 offset1:134
	ds_read_b128 v[182:185], v119 offset:3456
	ds_read_b128 v[186:189], v119 offset:3520
	ds_read_b128 v[190:193], v119 offset:5760
	ds_read_b128 v[194:197], v119 offset:5824
	v_add_u32_e32 v136, s68, v156
	v_add_u32_sdwa v165, s68, v141 dst_sel:DWORD dst_unused:UNUSED_PAD src0_sel:DWORD src1_sel:BYTE_2
	v_add_u32_sdwa v163, s68, v140 dst_sel:DWORD dst_unused:UNUSED_PAD src0_sel:DWORD src1_sel:BYTE_1
	v_add_u32_sdwa v215, s68, v141 dst_sel:DWORD dst_unused:UNUSED_PAD src0_sel:DWORD src1_sel:BYTE_3
	ds_read_b32 v136, v136 offset:41856
	ds_read_b32 v223, v163 offset:41856
	ds_read_b32 v165, v165 offset:41856
	ds_read_b32 v224, v215 offset:41856
	s_nop 0
	s_waitcnt vmcnt(5)
	v_mfma_f32_16x16x32_bf16 v[198:201], v[198:201], v[88:91], 0
	s_waitcnt vmcnt(4)
	v_mfma_f32_16x16x32_bf16 v[198:201], v[202:205], v[92:95], v[198:201]
	v_mfma_f32_16x16x32_bf16 v[202:205], v[206:209], v[88:91], 0
	v_mfma_f32_16x16x32_bf16 v[202:205], v[210:213], v[92:95], v[202:205]
	s_nop 0
	s_nop 6
	v_cndmask_b32_e64 v163, v198, v202, s[16:17]
	s_waitcnt lgkmcnt(14)
	v_add_f32_e32 v163, v217, v163
	v_cndmask_b32_e64 v198, v199, v203, s[18:19]
	v_cndmask_b32_e64 v200, v200, v204, s[6:7]
	v_exp_f32_e32 v163, v163
	v_add_f32_e32 v179, v179, v198
	s_waitcnt lgkmcnt(13)
	v_add_f32_e32 v200, v221, v200
	v_exp_f32_e32 v179, v179
	v_exp_f32_e32 v215, v200
	v_cndmask_b32_e64 v200, v201, v205, s[8:9]
	s_waitcnt lgkmcnt(12)
	v_add_f32_e32 v200, v222, v200
	v_exp_f32_e32 v217, v200
	v_cndmask_b32_e64 v198, v163, 0, s[16:17]
	v_cndmask_b32_e64 v202, 0, v163, s[16:17]
	v_pk_add_f32 v[162:163], v[162:163], 0 op_sel_hi:[1,0]
	v_cndmask_b32_e64 v199, v179, 0, s[18:19]
	v_pk_add_f32 v[162:163], v[178:179], v[162:163]
	v_cndmask_b32_e64 v200, 0, v179, s[18:19]
	v_pk_add_f32 v[162:163], v[214:215], v[162:163]
	v_cndmask_b32_e64 v201, v215, 0, s[6:7]
	v_pk_add_f32 v[162:163], v[216:217], v[162:163]
	v_cndmask_b32_e64 v203, 0, v215, s[6:7]
	v_pk_add_f32 v[130:131], v[130:131], v[162:163]
	v_cndmask_b32_e64 v204, v217, 0, s[8:9]
	v_cndmask_b32_e64 v205, 0, v217, s[8:9]
	v_cvt_pk_bf16_f32 v198, v198, v199
	v_cvt_pk_bf16_f32 v199, v201, v204
	v_cvt_pk_bf16_f32 v200, v202, v200
	v_cvt_pk_bf16_f32 v201, v203, v205
	s_nop 0
	s_waitcnt lgkmcnt(11)
	v_mfma_f32_16x16x32_bf16 v[44:47], v[158:161], v[198:201], v[44:47]
	s_waitcnt lgkmcnt(10)
	v_mfma_f32_16x16x32_bf16 v[40:43], v[166:169], v[198:201], v[40:43]
	s_waitcnt lgkmcnt(9)
	v_mfma_f32_16x16x32_bf16 v[36:39], v[170:173], v[198:201], v[36:39]
	s_waitcnt lgkmcnt(8)
	v_mfma_f32_16x16x32_bf16 v[32:35], v[174:177], v[198:201], v[32:35]
	s_nop 0
	ds_read2_b64 v[158:161], v181 offset0:134 offset1:138
	ds_read2_b64 v[166:169], v218 offset0:166 offset1:170
	ds_read2_b64 v[170:173], v219 offset0:198 offset1:202
	ds_read2_b64 v[174:177], v220 offset0:134 offset1:138
	ds_read_b128 v[198:201], v119 offset:4608
	ds_read_b128 v[202:205], v119 offset:4672
	v_add_u32_e32 v119, v148, v151
	ds_read_b128 v[206:209], v119
	ds_read_b128 v[210:213], v119 offset:64
	v_add_u32_e32 v119, s68, v154
	v_add_u32_sdwa v162, s68, v145 dst_sel:DWORD dst_unused:UNUSED_PAD src0_sel:DWORD src1_sel:BYTE_1
	v_add_u32_sdwa v163, s68, v146 dst_sel:DWORD dst_unused:UNUSED_PAD src0_sel:DWORD src1_sel:BYTE_2
	v_add_u32_sdwa v178, s68, v146 dst_sel:DWORD dst_unused:UNUSED_PAD src0_sel:DWORD src1_sel:BYTE_3
	ds_read_b32 v119, v119 offset:41856
	ds_read_b32 v179, v162 offset:41856
	ds_read_b32 v214, v163 offset:41856
	ds_read_b32 v215, v178 offset:41856
	s_nop 0
	s_waitcnt vmcnt(3) lgkmcnt(14)
	v_mfma_f32_16x16x32_bf16 v[182:185], v[182:185], v[96:99], 0
	s_waitcnt vmcnt(2)
	v_mfma_f32_16x16x32_bf16 v[182:185], v[186:189], v[100:103], v[182:185]
	v_mfma_f32_16x16x32_bf16 v[186:189], v[190:193], v[96:99], 0
	v_mfma_f32_16x16x32_bf16 v[186:189], v[194:197], v[100:103], v[186:189]
	s_nop 0
	s_nop 6
	v_cndmask_b32_e64 v162, v186, v182, s[2:3]
	v_add_f32_e32 v136, v136, v162
	v_exp_f32_e32 v162, v136
	v_cndmask_b32_e64 v136, v187, v183, s[4:5]
	v_cndmask_b32_e64 v183, v184, v188, s[22:23]
	s_waitcnt lgkmcnt(13)
	v_add_f32_e32 v165, v165, v183
	v_exp_f32_e32 v190, v165
	v_cndmask_b32_e64 v165, v185, v189, s[24:25]
	v_add_f32_e32 v136, v223, v136
	s_waitcnt lgkmcnt(12)
	v_add_f32_e32 v165, v224, v165
	v_exp_f32_e32 v178, v136
	v_exp_f32_e32 v192, v165
	v_cndmask_b32_e64 v183, v190, 0, s[22:23]
	v_cndmask_b32_e64 v185, 0, v190, s[22:23]
	v_cndmask_b32_e64 v182, 0, v178, s[4:5]
	v_cndmask_b32_e64 v184, v192, 0, s[24:25]
	v_cndmask_b32_e64 v136, 0, v162, s[2:3]
	v_cndmask_b32_e64 v163, v162, 0, s[2:3]
	v_cndmask_b32_e64 v165, v178, 0, s[4:5]
	v_cndmask_b32_e64 v186, 0, v192, s[24:25]
	v_cvt_pk_bf16_f32 v182, v136, v182
	v_cvt_pk_bf16_f32 v183, v183, v184
	v_cvt_pk_bf16_f32 v184, v163, v165
	v_cvt_pk_bf16_f32 v185, v185, v186
	s_nop 0
	s_waitcnt lgkmcnt(11)
	v_mfma_f32_16x16x32_bf16 v[28:31], v[158:161], v[182:185], v[28:31]
	s_waitcnt lgkmcnt(10)
	v_mfma_f32_16x16x32_bf16 v[24:27], v[166:169], v[182:185], v[24:27]
	s_waitcnt lgkmcnt(9)
	v_mfma_f32_16x16x32_bf16 v[20:23], v[170:173], v[182:185], v[20:23]
	s_waitcnt lgkmcnt(8)
	v_mfma_f32_16x16x32_bf16 v[16:19], v[174:177], v[182:185], v[16:19]
	s_nop 0
	ds_read2_b64 v[158:161], v220 offset0:136 offset1:140
	ds_read2_b64 v[166:169], v219 offset0:200 offset1:204
	ds_read2_b64 v[170:173], v218 offset0:168 offset1:172
	ds_read2_b64 v[174:177], v181 offset0:136 offset1:140
	s_nop 0
	s_waitcnt vmcnt(1) lgkmcnt(11)
	v_mfma_f32_16x16x32_bf16 v[182:185], v[198:201], v[104:107], 0
	s_waitcnt lgkmcnt(9)
	v_mfma_f32_16x16x32_bf16 v[186:189], v[206:209], v[104:107], 0
	s_waitcnt vmcnt(0)
	v_mfma_f32_16x16x32_bf16 v[182:185], v[202:205], v[108:111], v[182:185]
	s_waitcnt lgkmcnt(8)
	v_mfma_f32_16x16x32_bf16 v[186:189], v[210:213], v[108:111], v[186:189]
	s_nop 0
	s_nop 6
	v_cndmask_b32_e64 v136, v182, v186, s[26:27]
	s_waitcnt lgkmcnt(7)
	v_add_f32_e32 v119, v119, v136
	v_exp_f32_e32 v163, v119
	v_cndmask_b32_e64 v119, v183, v187, s[28:29]
	v_cndmask_b32_e64 v181, v184, v188, s[30:31]
	s_waitcnt lgkmcnt(6)
	v_add_f32_e32 v119, v179, v119
	s_waitcnt lgkmcnt(5)
	v_add_f32_e32 v181, v214, v181
	v_exp_f32_e32 v179, v119
	v_exp_f32_e32 v191, v181
	v_cndmask_b32_e64 v181, v185, v189, s[34:35]
	s_waitcnt lgkmcnt(4)
	v_add_f32_e32 v181, v215, v181
	v_exp_f32_e32 v193, v181
	v_cndmask_b32_e64 v119, v163, 0, s[26:27]
	v_cndmask_b32_e64 v136, 0, v163, s[26:27]
	v_pk_add_f32 v[162:163], v[162:163], 0 op_sel_hi:[1,0]
	v_cndmask_b32_e64 v183, v191, 0, s[30:31]
	v_pk_add_f32 v[162:163], v[178:179], v[162:163]
	v_cndmask_b32_e64 v185, 0, v191, s[30:31]
	v_pk_add_f32 v[162:163], v[190:191], v[162:163]
	v_cndmask_b32_e64 v184, v193, 0, s[34:35]
	v_pk_add_f32 v[162:163], v[192:193], v[162:163]
	v_cndmask_b32_e64 v165, v179, 0, s[28:29]
	v_pk_add_f32 v[124:125], v[124:125], v[162:163]
	v_cndmask_b32_e64 v181, 0, v179, s[28:29]
	v_cndmask_b32_e64 v186, 0, v193, s[34:35]
	v_cvt_pk_bf16_f32 v182, v119, v165
	v_cvt_pk_bf16_f32 v183, v183, v184
	v_cvt_pk_bf16_f32 v184, v136, v181
	v_cvt_pk_bf16_f32 v185, v185, v186
	s_nop 0
	s_waitcnt lgkmcnt(0)
	v_mfma_f32_16x16x32_bf16 v[12:15], v[174:177], v[182:185], v[12:15]
	v_mfma_f32_16x16x32_bf16 v[8:11], v[170:173], v[182:185], v[8:11]
	v_mfma_f32_16x16x32_bf16 v[4:7], v[166:169], v[182:185], v[4:7]
	v_mfma_f32_16x16x32_bf16 v[0:3], v[158:161], v[182:185], v[0:3]
	s_nop 0

.LBB0_597:
	s_add_i32 s66, s52, -2
	s_cmp_ge_u32 s66, s38
	s_cselect_b64 s[70:71], -1, 0
	s_cmp_lt_u32 s66, s39
	s_cselect_b64 s[72:73], -1, 0
	s_and_b64 s[70:71], s[70:71], s[72:73]
	s_andn2_b64 vcc, exec, s[70:71]
	s_cbranch_vccnz .LBB0_599
	v_add_u32_e32 v178, v150, v149
	v_add_u32_e32 v181, 0x6800, v178
	v_add_u32_e32 v218, 0x7000, v178
	v_add_u32_e32 v219, 0x7800, v178
	v_add_u32_e32 v178, v150, v151
	v_add_u32_e32 v119, v148, v149
	v_add_u32_e32 v136, s68, v152
	v_add_u32_sdwa v163, s68, v144 dst_sel:DWORD dst_unused:UNUSED_PAD src0_sel:DWORD src1_sel:BYTE_2
	v_add_u32_sdwa v165, s68, v144 dst_sel:DWORD dst_unused:UNUSED_PAD src0_sel:DWORD src1_sel:BYTE_3
	v_add_u32_e32 v220, 0x6800, v178
	v_add_u32_sdwa v179, s68, v142 dst_sel:DWORD dst_unused:UNUSED_PAD src0_sel:DWORD src1_sel:BYTE_1
	ds_read_b128 v[158:161], v119 offset:18432
	ds_read_b128 v[166:169], v119 offset:18496
	ds_read_b128 v[170:173], v119 offset:20736
	ds_read_b128 v[174:177], v119 offset:20800
	v_add_u32_e32 v162, s68, v153
	ds_read2_b64 v[182:185], v181 offset0:128 offset1:132
	ds_read2_b64 v[186:189], v218 offset0:160 offset1:164
	ds_read2_b64 v[190:193], v219 offset0:192 offset1:196
	ds_read2_b64 v[194:197], v220 offset0:128 offset1:132
	ds_read_b128 v[198:201], v119 offset:19584
	ds_read_b128 v[202:205], v119 offset:19648
	ds_read_b128 v[206:209], v119 offset:21888
	ds_read_b128 v[210:213], v119 offset:21952
	v_add_u32_e32 v178, s68, v155
	v_add_u32_sdwa v214, s68, v143 dst_sel:DWORD dst_unused:UNUSED_PAD src0_sel:DWORD src1_sel:BYTE_2
	v_add_u32_sdwa v215, s68, v143 dst_sel:DWORD dst_unused:UNUSED_PAD src0_sel:DWORD src1_sel:BYTE_3
	ds_read_b32 v136, v136 offset:41984
	ds_read_b32 v216, v162 offset:41984
	ds_read_b32 v163, v163 offset:41984
	ds_read_b32 v165, v165 offset:41984
	ds_read_b32 v217, v178 offset:41984
	ds_read_b32 v179, v179 offset:41984
	ds_read_b32 v221, v214 offset:41984
	ds_read_b32 v222, v215 offset:41984
	s_nop 0
	s_waitcnt vmcnt(7) lgkmcnt(14)
	v_mfma_f32_16x16x32_bf16 v[158:161], v[158:161], v[80:83], 0
	s_waitcnt vmcnt(6)
	v_mfma_f32_16x16x32_bf16 v[158:161], v[166:169], v[84:87], v[158:161]
	v_mfma_f32_16x16x32_bf16 v[166:169], v[170:173], v[80:83], 0
	v_mfma_f32_16x16x32_bf16 v[166:169], v[174:177], v[84:87], v[166:169]
	s_nop 0
	s_nop 6
	v_cndmask_b32_e64 v158, v166, v158, s[20:21]
	s_waitcnt lgkmcnt(7)
	v_add_f32_e32 v136, v136, v158
	v_exp_f32_e32 v162, v136
	v_cndmask_b32_e64 v136, v159, v167, s[10:11]
	v_cndmask_b32_e64 v159, v160, v168, s[12:13]
	s_waitcnt lgkmcnt(5)
	v_add_f32_e32 v159, v163, v159
	v_add_f32_e32 v136, v216, v136
	v_exp_f32_e32 v214, v159
	v_cndmask_b32_e64 v159, v161, v169, s[14:15]
	v_exp_f32_e32 v178, v136
	s_waitcnt lgkmcnt(4)
	v_add_f32_e32 v159, v165, v159
	v_exp_f32_e32 v216, v159
	v_cndmask_b32_e64 v159, v214, 0, s[12:13]
	v_cndmask_b32_e64 v158, v178, 0, s[10:11]
	v_cndmask_b32_e64 v160, 0, v178, s[10:11]
	v_cndmask_b32_e64 v161, 0, v214, s[12:13]
	v_cndmask_b32_e64 v136, 0, v162, s[20:21]
	v_cndmask_b32_e64 v166, v162, 0, s[20:21]
	v_cndmask_b32_e64 v163, v216, 0, s[14:15]
	v_cndmask_b32_e64 v165, 0, v216, s[14:15]
	v_cvt_pk_bf16_f32 v158, v136, v158
	v_cvt_pk_bf16_f32 v159, v159, v163
	v_cvt_pk_bf16_f32 v160, v166, v160
	v_cvt_pk_bf16_f32 v161, v161, v165
	s_nop 0
	v_mfma_f32_16x16x32_bf16 v[60:63], v[182:185], v[158:161], v[60:63]
	v_mfma_f32_16x16x32_bf16 v[56:59], v[186:189], v[158:161], v[56:59]
	v_mfma_f32_16x16x32_bf16 v[52:55], v[190:193], v[158:161], v[52:55]
	v_mfma_f32_16x16x32_bf16 v[48:51], v[194:197], v[158:161], v[48:51]
	s_nop 0
	ds_read2_b64 v[158:161], v181 offset0:130 offset1:134
	ds_read2_b64 v[166:169], v218 offset0:162 offset1:166
	ds_read2_b64 v[170:173], v219 offset0:194 offset1:198
	ds_read2_b64 v[174:177], v220 offset0:130 offset1:134
	ds_read_b128 v[182:185], v119 offset:21888
	ds_read_b128 v[186:189], v119 offset:21952
	ds_read_b128 v[190:193], v119 offset:24192
	ds_read_b128 v[194:197], v119 offset:24256
	v_add_u32_e32 v136, s68, v156
	v_add_u32_sdwa v165, s68, v141 dst_sel:DWORD dst_unused:UNUSED_PAD src0_sel:DWORD src1_sel:BYTE_2
	v_add_u32_sdwa v163, s68, v140 dst_sel:DWORD dst_unused:UNUSED_PAD src0_sel:DWORD src1_sel:BYTE_1
	v_add_u32_sdwa v215, s68, v141 dst_sel:DWORD dst_unused:UNUSED_PAD src0_sel:DWORD src1_sel:BYTE_3
	ds_read_b32 v136, v136 offset:41984
	ds_read_b32 v223, v163 offset:41984
	ds_read_b32 v165, v165 offset:41984
	ds_read_b32 v224, v215 offset:41984
	s_nop 0
	s_waitcnt vmcnt(5)
	v_mfma_f32_16x16x32_bf16 v[198:201], v[198:201], v[88:91], 0
	s_waitcnt vmcnt(4)
	v_mfma_f32_16x16x32_bf16 v[198:201], v[202:205], v[92:95], v[198:201]
	v_mfma_f32_16x16x32_bf16 v[202:205], v[206:209], v[88:91], 0
	v_mfma_f32_16x16x32_bf16 v[202:205], v[210:213], v[92:95], v[202:205]
	s_nop 0
	s_nop 6
	v_cndmask_b32_e64 v163, v198, v202, s[16:17]
	s_waitcnt lgkmcnt(14)
	v_add_f32_e32 v163, v217, v163
	v_cndmask_b32_e64 v198, v199, v203, s[18:19]
	v_cndmask_b32_e64 v200, v200, v204, s[6:7]
	v_exp_f32_e32 v163, v163
	v_add_f32_e32 v179, v179, v198
	s_waitcnt lgkmcnt(13)
	v_add_f32_e32 v200, v221, v200
	v_exp_f32_e32 v179, v179
	v_exp_f32_e32 v215, v200
	v_cndmask_b32_e64 v200, v201, v205, s[8:9]
	s_waitcnt lgkmcnt(12)
	v_add_f32_e32 v200, v222, v200
	v_exp_f32_e32 v217, v200
	v_cndmask_b32_e64 v198, v163, 0, s[16:17]
	v_cndmask_b32_e64 v202, 0, v163, s[16:17]
	v_pk_add_f32 v[162:163], v[162:163], 0 op_sel_hi:[1,0]
	v_cndmask_b32_e64 v199, v179, 0, s[18:19]
	v_pk_add_f32 v[162:163], v[178:179], v[162:163]
	v_cndmask_b32_e64 v200, 0, v179, s[18:19]
	v_pk_add_f32 v[162:163], v[214:215], v[162:163]
	v_cndmask_b32_e64 v201, v215, 0, s[6:7]
	v_pk_add_f32 v[162:163], v[216:217], v[162:163]
	v_cndmask_b32_e64 v203, 0, v215, s[6:7]
	v_pk_add_f32 v[130:131], v[130:131], v[162:163]
	v_cndmask_b32_e64 v204, v217, 0, s[8:9]
	v_cndmask_b32_e64 v205, 0, v217, s[8:9]
	v_cvt_pk_bf16_f32 v198, v198, v199
	v_cvt_pk_bf16_f32 v199, v201, v204
	v_cvt_pk_bf16_f32 v200, v202, v200
	v_cvt_pk_bf16_f32 v201, v203, v205
	s_nop 0
	s_waitcnt lgkmcnt(11)
	v_mfma_f32_16x16x32_bf16 v[44:47], v[158:161], v[198:201], v[44:47]
	s_waitcnt lgkmcnt(10)
	v_mfma_f32_16x16x32_bf16 v[40:43], v[166:169], v[198:201], v[40:43]
	s_waitcnt lgkmcnt(9)
	v_mfma_f32_16x16x32_bf16 v[36:39], v[170:173], v[198:201], v[36:39]
	s_waitcnt lgkmcnt(8)
	v_mfma_f32_16x16x32_bf16 v[32:35], v[174:177], v[198:201], v[32:35]
	s_nop 0
	ds_read2_b64 v[158:161], v181 offset0:134 offset1:138
	ds_read2_b64 v[166:169], v218 offset0:166 offset1:170
	ds_read2_b64 v[170:173], v219 offset0:198 offset1:202
	ds_read2_b64 v[174:177], v220 offset0:134 offset1:138
	ds_read_b128 v[198:201], v119 offset:23040
	ds_read_b128 v[202:205], v119 offset:23104
	v_add_u32_e32 v119, v148, v151
	ds_read_b128 v[206:209], v119 offset:18432
	ds_read_b128 v[210:213], v119 offset:18496
	v_add_u32_e32 v119, s68, v154
	v_add_u32_sdwa v162, s68, v145 dst_sel:DWORD dst_unused:UNUSED_PAD src0_sel:DWORD src1_sel:BYTE_1
	v_add_u32_sdwa v163, s68, v146 dst_sel:DWORD dst_unused:UNUSED_PAD src0_sel:DWORD src1_sel:BYTE_2
	v_add_u32_sdwa v178, s68, v146 dst_sel:DWORD dst_unused:UNUSED_PAD src0_sel:DWORD src1_sel:BYTE_3
	ds_read_b32 v119, v119 offset:41984
	ds_read_b32 v179, v162 offset:41984
	ds_read_b32 v214, v163 offset:41984
	ds_read_b32 v215, v178 offset:41984
	s_nop 0
	s_waitcnt vmcnt(3) lgkmcnt(14)
	v_mfma_f32_16x16x32_bf16 v[182:185], v[182:185], v[96:99], 0
	s_waitcnt vmcnt(2)
	v_mfma_f32_16x16x32_bf16 v[182:185], v[186:189], v[100:103], v[182:185]
	v_mfma_f32_16x16x32_bf16 v[186:189], v[190:193], v[96:99], 0
	v_mfma_f32_16x16x32_bf16 v[186:189], v[194:197], v[100:103], v[186:189]
	s_nop 0
	s_nop 6
	v_cndmask_b32_e64 v162, v186, v182, s[2:3]
	v_add_f32_e32 v136, v136, v162
	v_exp_f32_e32 v162, v136
	v_cndmask_b32_e64 v136, v187, v183, s[4:5]
	v_cndmask_b32_e64 v183, v184, v188, s[22:23]
	s_waitcnt lgkmcnt(13)
	v_add_f32_e32 v165, v165, v183
	v_exp_f32_e32 v190, v165
	v_cndmask_b32_e64 v165, v185, v189, s[24:25]
	v_add_f32_e32 v136, v223, v136
	s_waitcnt lgkmcnt(12)
	v_add_f32_e32 v165, v224, v165
	v_exp_f32_e32 v178, v136
	v_exp_f32_e32 v192, v165
	v_cndmask_b32_e64 v183, v190, 0, s[22:23]
	v_cndmask_b32_e64 v185, 0, v190, s[22:23]
	v_cndmask_b32_e64 v182, 0, v178, s[4:5]
	v_cndmask_b32_e64 v184, v192, 0, s[24:25]
	v_cndmask_b32_e64 v136, 0, v162, s[2:3]
	v_cndmask_b32_e64 v163, v162, 0, s[2:3]
	v_cndmask_b32_e64 v165, v178, 0, s[4:5]
	v_cndmask_b32_e64 v186, 0, v192, s[24:25]
	v_cvt_pk_bf16_f32 v182, v136, v182
	v_cvt_pk_bf16_f32 v183, v183, v184
	v_cvt_pk_bf16_f32 v184, v163, v165
	v_cvt_pk_bf16_f32 v185, v185, v186
	s_nop 0
	s_waitcnt lgkmcnt(11)
	v_mfma_f32_16x16x32_bf16 v[28:31], v[158:161], v[182:185], v[28:31]
	s_waitcnt lgkmcnt(10)
	v_mfma_f32_16x16x32_bf16 v[24:27], v[166:169], v[182:185], v[24:27]
	s_waitcnt lgkmcnt(9)
	v_mfma_f32_16x16x32_bf16 v[20:23], v[170:173], v[182:185], v[20:23]
	s_waitcnt lgkmcnt(8)
	v_mfma_f32_16x16x32_bf16 v[16:19], v[174:177], v[182:185], v[16:19]
	s_nop 0
	ds_read2_b64 v[158:161], v220 offset0:136 offset1:140
	ds_read2_b64 v[166:169], v219 offset0:200 offset1:204
	ds_read2_b64 v[170:173], v218 offset0:168 offset1:172
	ds_read2_b64 v[174:177], v181 offset0:136 offset1:140
	s_nop 0
	s_waitcnt vmcnt(1) lgkmcnt(11)
	v_mfma_f32_16x16x32_bf16 v[182:185], v[198:201], v[104:107], 0
	s_waitcnt lgkmcnt(9)
	v_mfma_f32_16x16x32_bf16 v[186:189], v[206:209], v[104:107], 0
	s_waitcnt vmcnt(0)
	v_mfma_f32_16x16x32_bf16 v[182:185], v[202:205], v[108:111], v[182:185]
	s_waitcnt lgkmcnt(8)
	v_mfma_f32_16x16x32_bf16 v[186:189], v[210:213], v[108:111], v[186:189]
	s_nop 0
	s_nop 6
	v_cndmask_b32_e64 v136, v182, v186, s[26:27]
	s_waitcnt lgkmcnt(7)
	v_add_f32_e32 v119, v119, v136
	v_exp_f32_e32 v163, v119
	v_cndmask_b32_e64 v119, v183, v187, s[28:29]
	v_cndmask_b32_e64 v181, v184, v188, s[30:31]
	s_waitcnt lgkmcnt(6)
	v_add_f32_e32 v119, v179, v119
	s_waitcnt lgkmcnt(5)
	v_add_f32_e32 v181, v214, v181
	v_exp_f32_e32 v179, v119
	v_exp_f32_e32 v191, v181
	v_cndmask_b32_e64 v181, v185, v189, s[34:35]
	s_waitcnt lgkmcnt(4)
	v_add_f32_e32 v181, v215, v181
	v_exp_f32_e32 v193, v181
	v_cndmask_b32_e64 v119, v163, 0, s[26:27]
	v_cndmask_b32_e64 v136, 0, v163, s[26:27]
	v_pk_add_f32 v[162:163], v[162:163], 0 op_sel_hi:[1,0]
	v_cndmask_b32_e64 v183, v191, 0, s[30:31]
	v_pk_add_f32 v[162:163], v[178:179], v[162:163]
	v_cndmask_b32_e64 v185, 0, v191, s[30:31]
	v_pk_add_f32 v[162:163], v[190:191], v[162:163]
	v_cndmask_b32_e64 v184, v193, 0, s[34:35]
	v_pk_add_f32 v[162:163], v[192:193], v[162:163]
	v_cndmask_b32_e64 v165, v179, 0, s[28:29]
	v_pk_add_f32 v[124:125], v[124:125], v[162:163]
	v_cndmask_b32_e64 v181, 0, v179, s[28:29]
	v_cndmask_b32_e64 v186, 0, v193, s[34:35]
	v_cvt_pk_bf16_f32 v182, v119, v165
	v_cvt_pk_bf16_f32 v183, v183, v184
	v_cvt_pk_bf16_f32 v184, v136, v181
	v_cvt_pk_bf16_f32 v185, v185, v186
	s_nop 0
	s_waitcnt lgkmcnt(0)
	v_mfma_f32_16x16x32_bf16 v[12:15], v[174:177], v[182:185], v[12:15]
	v_mfma_f32_16x16x32_bf16 v[8:11], v[170:173], v[182:185], v[8:11]
	v_mfma_f32_16x16x32_bf16 v[4:7], v[166:169], v[182:185], v[4:7]
	v_mfma_f32_16x16x32_bf16 v[0:3], v[158:161], v[182:185], v[0:3]
	s_nop 0

.LBB0_665:
	s_andn2_b64 vcc, exec, s[48:49]
	s_cbranch_vccnz .LBB0_710
	v_lshrrev_b32_e32 v0, 5, v180
	v_and_b32_e32 v7, 31, v180
	v_mul_u32_u24_e32 v0, 31, v0
	v_add3_u32 v0, s97, v0, v7
	v_lshlrev_b32_e32 v0, 2, v0
	v_cmp_ne_u32_e32 vcc, 31, v7
	v_lshlrev_b32_e32 v16, 2, v180
	v_mov_b32_e32 v20, 0
	v_mov_b32_e32 v21, 0
	v_mov_b32_e32 v22, 0
	v_mov_b32_e32 v23, 0
	v_mov_b32_e32 v24, 0
	v_mov_b32_e32 v25, 0
	v_mov_b32_e32 v26, 0
	v_mov_b32_e32 v27, 0
	s_waitcnt lgkmcnt(0)
	global_load_dword v2, v16, s[40:41]
	global_load_dword v3, v16, s[42:43]
	s_mov_b64 s[2:3], exec
	v_cmp_gt_u32_e64 s[0:1], 32, v180
	s_and_b64 exec, exec, vcc
	global_load_dword v20, v0, s[46:47]
	global_load_dword v21, v0, s[46:47] offset:248
	global_load_dword v22, v0, s[46:47] offset:496
	global_load_dword v23, v0, s[46:47] offset:744
	global_load_dword v24, v0, s[46:47] offset:992
	global_load_dword v25, v0, s[46:47] offset:1240
	global_load_dword v26, v0, s[46:47] offset:1488
	s_and_b64 exec, exec, s[0:1]
	global_load_dword v27, v0, s[46:47] offset:1736
	s_mov_b64 exec, s[2:3]
	v_xor_b32_e32 v8, 1, v180
	v_lshlrev_b32_e32 v8, 2, v8
	v_xor_b32_e32 v9, 2, v180
	v_lshlrev_b32_e32 v9, 2, v9
	v_xor_b32_e32 v10, 4, v180
	v_lshlrev_b32_e32 v10, 2, v10
	v_xor_b32_e32 v11, 8, v180
	v_lshlrev_b32_e32 v11, 2, v11
	v_xor_b32_e32 v138, 16, v180
	v_lshlrev_b32_e32 v138, 2, v138
	v_xor_b32_e32 v139, 32, v180
	v_lshlrev_b32_e32 v139, 2, v139
	s_mul_i32 s5, s92, 0x780
	v_add_u32_e32 v16, s5, v16
	v_add_u32_e32 v16, 0xa000, v16
	s_waitcnt vmcnt(8)
	v_max_f32_e64 v5, |v2|, |v2|
	v_max_f32_e64 v6, |v3|, |v3|
	s_waitcnt vmcnt(0)
	v_max_f32_e64 v1, |v20|, |v21|
	v_max_f32_e64 v4, |v22|, |v23|
	v_max_f32_e64 v12, |v24|, |v25|
	v_max_f32_e64 v13, |v26|, |v27|
	v_max_f32_e32 v1, v1, v4
	v_max_f32_e32 v12, v12, v13
	v_max_f32_e32 v1, v1, v12
	ds_bpermute_b32 v12, v8, v1
	ds_bpermute_b32 v13, v8, v5
	ds_bpermute_b32 v14, v8, v6
	s_waitcnt lgkmcnt(0)
	v_max_f32_e32 v1, v1, v12
	v_max_f32_e32 v5, v5, v13
	v_max_f32_e32 v6, v6, v14
	ds_bpermute_b32 v12, v9, v1
	ds_bpermute_b32 v13, v9, v5
	ds_bpermute_b32 v14, v9, v6
	s_waitcnt lgkmcnt(0)
	v_max_f32_e32 v1, v1, v12
	v_max_f32_e32 v5, v5, v13
	v_max_f32_e32 v6, v6, v14
	ds_bpermute_b32 v12, v10, v1
	ds_bpermute_b32 v13, v10, v5
	ds_bpermute_b32 v14, v10, v6
	s_waitcnt lgkmcnt(0)
	v_max_f32_e32 v1, v1, v12
	v_max_f32_e32 v5, v5, v13
	v_max_f32_e32 v6, v6, v14
	ds_bpermute_b32 v12, v11, v1
	ds_bpermute_b32 v13, v11, v5
	ds_bpermute_b32 v14, v11, v6
	s_waitcnt lgkmcnt(0)
	v_max_f32_e32 v1, v1, v12
	v_max_f32_e32 v5, v5, v13
	v_max_f32_e32 v6, v6, v14
	ds_bpermute_b32 v12, v138, v1
	ds_bpermute_b32 v13, v138, v5
	ds_bpermute_b32 v14, v138, v6
	s_waitcnt lgkmcnt(0)
	v_max_f32_e32 v1, v1, v12
	v_max_f32_e32 v5, v5, v13
	v_max_f32_e32 v6, v6, v14
	ds_bpermute_b32 v12, v139, v1
	ds_bpermute_b32 v13, v139, v5
	ds_bpermute_b32 v14, v139, v6
	s_waitcnt lgkmcnt(0)
	v_max_f32_e32 v1, v1, v12
	v_max_f32_e32 v5, v5, v13
	v_max_f32_e32 v6, v6, v14
	v_mul_f32_e32 v5, 0x41000000, v5
	v_fmac_f32_e32 v1, v6, v5
	v_mov_b32_e32 v15, 0xf149f2ca
	v_sub_f32_e32 v12, v20, v1
	v_mul_f32_e32 v12, 0x3fb8aa3b, v12
	v_cndmask_b32_e32 v12, v15, v12, vcc
	ds_write_b32 v16, v12
	v_sub_f32_e32 v12, v21, v1
	v_mul_f32_e32 v12, 0x3fb8aa3b, v12
	v_cndmask_b32_e32 v12, v15, v12, vcc
	ds_write_b32 v16, v12 offset:256
	v_sub_f32_e32 v12, v22, v1
	v_mul_f32_e32 v12, 0x3fb8aa3b, v12
	v_cndmask_b32_e32 v12, v15, v12, vcc
	ds_write_b32 v16, v12 offset:512
	v_sub_f32_e32 v12, v23, v1
	v_mul_f32_e32 v12, 0x3fb8aa3b, v12
	v_cndmask_b32_e32 v12, v15, v12, vcc
	ds_write_b32 v16, v12 offset:768
	v_sub_f32_e32 v12, v24, v1
	v_mul_f32_e32 v12, 0x3fb8aa3b, v12
	v_cndmask_b32_e32 v12, v15, v12, vcc
	ds_write_b32 v16, v12 offset:1024
	v_sub_f32_e32 v12, v25, v1
	v_mul_f32_e32 v12, 0x3fb8aa3b, v12
	v_cndmask_b32_e32 v12, v15, v12, vcc
	ds_write_b32 v16, v12 offset:1280
	v_sub_f32_e32 v12, v26, v1
	v_mul_f32_e32 v12, 0x3fb8aa3b, v12
	v_cndmask_b32_e32 v12, v15, v12, vcc
	ds_write_b32 v16, v12 offset:1536
	v_sub_f32_e32 v12, v27, v1
	v_mul_f32_e32 v12, 0x3fb8aa3b, v12
	v_cndmask_b32_e32 v12, v15, v12, vcc
	s_and_b64 exec, exec, s[0:1]
	ds_write_b32 v16, v12 offset:1792
	s_mov_b64 exec, s[2:3]
	s_cmp_ge_u32 s92, 4
	s_cbranch_scc0 .Lprio_a3
	s_setprio 1
.Lprio_a3:
	s_mov_b64 s[2:3], -1
.LBB0_672:
	s_or_b64 exec, exec, s[2:3]
	s_abs_i32 s0, s84
	v_cvt_f32_u32_e32 v0, s0
	s_sub_i32 s3, 0, s0
	s_add_i32 s1, s84, 0x4ff
	s_xor_b32 s2, s1, s84
	v_rcp_iflag_f32_e32 v0, v0
	s_abs_i32 s1, s1
	s_ashr_i32 s2, s2, 31
	s_mov_b32 s41, 0
	v_mul_f32_e32 v0, 0x4f7ffffe, v0
	v_cvt_u32_f32_e32 v0, v0
	s_waitcnt lgkmcnt(0)
	s_barrier
	v_readfirstlane_b32 s4, v0
	s_mul_i32 s3, s3, s4
	s_mul_hi_u32 s3, s4, s3
	s_add_i32 s4, s4, s3
	s_mul_hi_u32 s3, s1, s4
	s_mul_i32 s4, s3, s0
	s_sub_i32 s1, s1, s4
	s_add_i32 s5, s3, 1
	s_sub_i32 s4, s1, s0
	s_cmp_ge_u32 s1, s0
	s_cselect_b32 s3, s5, s3
	s_cselect_b32 s1, s4, s1
	s_add_i32 s4, s3, 1
	s_cmp_ge_u32 s1, s0
	s_cselect_b32 s0, s4, s3
	s_xor_b32 s0, s0, s2
	s_sub_i32 s0, s0, s2
	s_mul_i32 s1, s0, s33
	s_min_i32 s0, s0, 0x100000
	s_add_i32 s64, s1, 3
	s_add_i32 s1, s1, s0
	s_min_i32 s65, s1, 0x500
	s_cmp_lt_i32 s64, s65
	s_cbranch_scc0 .LBB0_709
	v_lshrrev_b32_e32 v1, 2, v180
	v_and_b32_e32 v2, 12, v1
	v_add_u32_e32 v13, 26, v2
	v_add_u32_e32 v14, 24, v137
	v_sub_u32_e32 v15, v13, v14
	v_mov_b32_e32 v16, 0x400
	v_cmp_gt_u32_e32 vcc, 16, v15
	v_mov_b32_e32 v18, 0x800
	v_mov_b32_e32 v19, 0x200
	v_cndmask_b32_e32 v15, 0, v16, vcc
	v_add_u32_e32 v16, 27, v2
	v_sub_u32_e32 v17, v16, v14
	v_cmp_gt_u32_e64 s[0:1], 16, v17
	v_sub_u32_e64 v0, v137, 8 clamp
	v_or_b32_e32 v4, 1, v2
	v_cndmask_b32_e64 v17, 0, v18, s[0:1]
	v_add_u32_e32 v18, 25, v2
	v_sub_u32_e32 v14, v18, v14
	v_cmp_gt_u32_e64 s[4:5], 16, v14
	v_or_b32_e32 v6, 2, v2
	v_or_b32_e32 v8, 3, v1
	v_add_u32_e32 v9, 8, v137
	v_add_u32_e32 v11, 9, v2
	v_cndmask_b32_e64 v14, 0, v19, s[4:5]
	v_add_u32_e32 v19, 10, v2
	v_add_u32_e32 v21, 11, v2
	v_sub_u32_e32 v3, v2, v0
	v_sub_u32_e32 v5, v4, v0
	v_sub_u32_e32 v7, v6, v0
	v_sub_u32_e32 v0, v8, v0
	v_sub_u32_e32 v10, v2, v137
	v_sub_u32_e32 v12, v11, v9
	v_sub_u32_e32 v20, v19, v9
	v_sub_u32_e32 v9, v21, v9
	v_mov_b32_e32 v22, 0x80
	v_cmp_lt_u32_e64 s[8:9], 15, v9
	v_cmp_lt_u32_e64 s[14:15], 15, v0
	v_cmp_lt_u32_e64 s[16:17], 15, v10
	v_cmp_gt_u32_e64 s[2:3], 16, v10
	v_cmp_lt_u32_e64 s[6:7], 15, v20
	v_cndmask_b32_e64 v9, v22, 0, s[8:9]
	v_cmp_lt_u32_e64 s[10:11], 15, v5
	v_cndmask_b32_e64 v0, 8, 0, s[14:15]
	v_cndmask_b32_e64 v10, 16, 0, s[16:17]
	v_cndmask_b32_e64 v20, 64, 0, s[6:7]
	v_cndmask_b32_e64 v5, 2, 0, s[10:11]
	v_cmp_lt_u32_e64 s[12:13], 15, v7
	v_cmp_lt_u32_e64 s[18:19], 15, v12
	v_or3_b32 v0, v0, v10, v9
	v_or_b32_e32 v15, v15, v17
	v_mov_b32_e32 v17, 0x100
	v_cndmask_b32_e64 v7, 4, 0, s[12:13]
	v_cndmask_b32_e64 v12, 32, 0, s[18:19]
	v_or3_b32 v0, v5, v20, v0
	v_cndmask_b32_e64 v17, 0, v17, s[2:3]
	v_or3_b32 v0, v7, v12, v0
	v_or3_b32 v5, v17, v0, v14
	v_add_u32_e32 v0, 42, v2
	v_add_u32_e32 v12, 43, v2
	v_add_u32_e32 v17, 41, v2
	v_cndmask_b32_e32 v0, v0, v13, vcc
	v_or_b32_e32 v9, 32, v137
	v_cndmask_b32_e64 v12, v12, v16, s[0:1]
	v_cndmask_b32_e64 v17, v17, v18, s[4:5]
	v_sub_u32_e32 v0, v0, v9
	v_sub_u32_e32 v12, v12, v9
	v_sub_u32_e32 v17, v17, v9
	v_cndmask_b32_e64 v22, 40, 24, s[2:3]
	v_sub_u32_e32 v9, v2, v9
	v_mov_b32_e32 v20, 0x3c00
	v_add_u32_e32 v9, v9, v22
	v_mov_b32_e32 v10, 0x3c0000
	v_bfrev_b32_e32 v14, 60
	v_lshl_add_u32 v17, v17, 10, v20
	v_lshl_add_u32 v9, v9, 2, 60
	v_lshl_add_u32 v0, v0, 18, v10
	v_lshl_add_u32 v12, v12, 26, v14
	v_or_b32_e32 v140, v17, v9
	v_or3_b32 v141, v0, v12, v140
	v_cndmask_b32_e64 v0, v19, v13, s[6:7]
	v_or_b32_e32 v9, 16, v137
	v_cndmask_b32_e64 v12, v21, v16, s[8:9]
	v_cndmask_b32_e64 v11, v11, v18, s[18:19]
	v_sub_u32_e32 v0, v0, v9
	v_sub_u32_e32 v12, v12, v9
	v_sub_u32_e32 v11, v11, v9
	v_cndmask_b32_e64 v13, 8, 24, s[16:17]
	v_sub_u32_e32 v9, v2, v9
	v_add_u32_e32 v9, v9, v13
	v_lshl_add_u32 v11, v11, 10, v20
	v_lshl_add_u32 v9, v9, 2, 60
	v_lshl_add_u32 v0, v0, 18, v10
	v_lshl_add_u32 v12, v12, 26, v14
	v_or_b32_e32 v142, v11, v9
	v_or3_b32 v143, v0, v12, v142
	v_or_b32_e32 v0, 18, v2
	v_cndmask_b32_e64 v0, v6, v0, s[12:13]
	v_or_b32_e32 v6, 19, v1
	v_cndmask_b32_e64 v6, v8, v6, s[14:15]
	v_or_b32_e32 v8, 17, v2
	v_cndmask_b32_e64 v4, v4, v8, s[10:11]
	v_or_b32_e32 v8, 16, v2
	v_cmp_gt_u32_e64 s[20:21], 16, v3
	v_sub_u32_e32 v4, v4, v137
	v_sub_u32_e32 v0, v0, v137
	v_cndmask_b32_e64 v3, v8, v2, s[20:21]
	v_sub_u32_e32 v3, v3, v137
	v_sub_u32_e32 v6, v6, v137
	v_lshl_add_u32 v4, v4, 10, v20
	v_lshl_add_u32 v3, v3, 2, 60
	v_lshl_add_u32 v0, v0, 18, v10
	v_lshl_add_u32 v6, v6, 26, v14
	v_or_b32_e32 v4, v4, v3
	v_or3_b32 v144, v0, v6, v4
	v_or_b32_e32 v6, 48, v180
	v_add_u32_e32 v8, -8, v6
	v_or_b32_e32 v0, 35, v1
	v_min_u32_e32 v8, 48, v8
	v_sub_u32_e32 v9, v0, v8
	v_mov_b32_e32 v11, 0x8000
	v_cmp_gt_u32_e32 vcc, 16, v9
	v_mov_b32_e32 v16, 0x4000
	v_or_b32_e32 v1, 51, v1
	v_cndmask_b32_e32 v9, 0, v11, vcc
	v_or_b32_e32 v11, 34, v2
	v_sub_u32_e32 v12, v11, v8
	v_cmp_gt_u32_e64 s[0:1], 16, v12
	v_mov_b32_e32 v18, 0x2000
	v_cndmask_b32_e32 v0, v1, v0, vcc
	v_cndmask_b32_e64 v12, 0, v16, s[0:1]
	v_or_b32_e32 v16, 33, v2
	v_sub_u32_e32 v17, v16, v8
	v_cmp_gt_u32_e64 s[22:23], 16, v17
	v_or_b32_e32 v1, 50, v2
	v_cndmask_b32_e64 v1, v1, v11, s[0:1]
	v_cndmask_b32_e64 v17, 0, v18, s[22:23]
	v_or_b32_e32 v18, 32, v2
	v_sub_u32_e32 v8, v18, v8
	v_sub_u32_e32 v1, v1, v6
	v_cmp_gt_u32_e64 s[24:25], 16, v8
	v_lshl_add_u32 v1, v1, 18, v10
	v_or_b32_e32 v10, 49, v2
	v_or_b32_e32 v2, 48, v2
	v_cndmask_b32_e64 v10, v10, v16, s[22:23]
	v_cndmask_b32_e64 v2, v2, v18, s[24:25]
	v_sub_u32_e32 v10, v10, v6
	v_sub_u32_e32 v2, v2, v6
	v_sub_u32_e32 v0, v0, v6
	v_lshl_add_u32 v10, v10, 10, v20
	v_lshl_add_u32 v2, v2, 2, 60
	v_lshl_add_u32 v0, v0, 26, v14
	v_or_b32_e32 v145, v10, v2
	v_or3_b32 v146, v1, v0, v145
	v_and_b32_e32 v1, 7, v164
	v_mov_b32_e32 v19, 0x1000
	v_lshrrev_b32_e32 v147, 3, v164
	v_lshlrev_b32_e32 v114, 4, v1
	s_movk_i32 s0, 0x90
	s_movk_i32 s26, 0x400
	s_movk_i32 s27, 0x800
	v_cndmask_b32_e64 v8, 0, v19, s[24:25]
	v_lshlrev_b32_e32 v0, 3, v1
	v_lshrrev_b32_e32 v1, 4, v180
	v_mad_u32_u24 v10, v147, s0, v114
	s_add_u32 s0, s80, 0x11000000
	v_and_b32_e32 v112, 48, v180
	v_or_b32_e32 v7, v15, v5
	s_movk_i32 s29, 0x1000
	v_or_b32_e32 v8, v8, v17
	v_lshl_add_u32 v150, v1, 3, 0
	v_mul_u32_u24_e32 v151, 0x90, v6
	v_bitop3_b32 v6, v15, s26, v5 bitop3:0xc8
	v_bitop3_b32 v5, v15, s27, v5 bitop3:0xc8
	v_and_b32_e32 v152, 0xfc, v3
	v_and_b32_e32 v154, 0xfc, v2
	v_lshlrev_b32_e32 v2, 2, v1
	s_addc_u32 s1, s81, 0
	v_lshl_add_u32 v1, v13, 2, v112
	v_lshlrev_b32_e32 v3, 2, v137
	s_movk_i32 s28, 0x2000
	v_cmp_eq_u32_e64 s[24:25], 0, v5
	v_bitop3_b32 v5, v8, s29, v7 bitop3:0xc8
	s_add_u32 s42, s80, 0x50000
	v_sub_u32_e32 v1, v1, v3
	s_movk_i32 s30, 0x4000
	v_or_b32_e32 v17, v8, v7
	v_or_b32_e32 v9, v12, v9
	v_cmp_eq_u32_e64 s[26:27], 0, v5
	v_bitop3_b32 v5, v8, s28, v7 bitop3:0xc8
	s_addc_u32 s43, s81, 0
	v_add_u32_e32 v1, -4, v1
	s_mov_b32 s34, 0x8000
	v_cmp_eq_u32_e64 s[28:29], 0, v5
	v_bitop3_b32 v5, v9, s30, v17 bitop3:0xc8
	s_add_u32 s66, s80, 0x17000000
	v_and_b32_e32 v155, 0xfc, v1
	v_lshl_add_u32 v1, v22, 2, v112
	v_mov_b32_e32 v113, 0
	v_cmp_eq_u32_e64 s[30:31], 0, v5
	v_bitop3_b32 v5, v9, s34, v17 bitop3:0xc8
	s_addc_u32 s67, s81, 0
	v_sub_u32_e32 v1, v1, v3
	v_and_b32_e32 v11, 48, v164
	v_cmp_eq_u32_e64 s[34:35], 0, v5
	v_lshrrev_b32_e32 v153, 8, v4
	v_lshl_add_u64 v[4:5], s[80:81], 0, v[112:113]
	s_mov_b64 s[38:39], 0xc000000
	s_add_u32 s68, s80, 0x16000000
	v_add_u32_e32 v1, 0xffffffbc, v1
	v_add_u32_e32 v148, 0, v11
	v_mul_u32_u24_e32 v149, 0x90, v137
	v_cmp_eq_u32_e64 s[22:23], 0, v6
	v_cmp_gt_u32_e64 s[36:37], 16, v180
	v_lshl_add_u64 v[116:117], v[4:5], 0, s[38:39]
	s_addc_u32 s69, s81, 0
	v_mov_b32_e32 v115, v113
	v_and_b32_e32 v156, 0xfc, v1
	v_lshlrev_b32_e32 v112, 1, v0
	s_mov_b64 s[46:47], 0x20000
	s_mov_b64 s[48:49], 0x100
	v_lshlrev_b32_e32 v118, 1, v2
	s_mov_b64 s[50:51], 0x39000000
	s_mov_b32 s70, 0x500000
	v_add_u32_e32 v157, 0, v10
	s_branch .LBB0_675

.LBB0_690:
	s_add_i32 s62, s40, -3
	s_cmp_ge_u32 s62, s38
	s_cselect_b64 s[52:53], -1, 0
	s_cmp_lt_u32 s62, s39
	s_cselect_b64 s[74:75], -1, 0
	s_and_b64 s[52:53], s[52:53], s[74:75]
	s_andn2_b64 vcc, exec, s[52:53]
	s_cbranch_vccnz .LBB0_692
	v_add_u32_e32 v178, v150, v149
	v_add_u32_e32 v181, 0x2000, v178
	v_add_u32_e32 v218, 0x2800, v178
	v_add_u32_e32 v219, 0x3000, v178
	v_add_u32_e32 v178, v150, v151
	v_add_u32_e32 v119, v148, v149
	v_add_u32_e32 v136, s60, v152
	v_add_u32_sdwa v163, s60, v144 dst_sel:DWORD dst_unused:UNUSED_PAD src0_sel:DWORD src1_sel:BYTE_2
	v_add_u32_sdwa v165, s60, v144 dst_sel:DWORD dst_unused:UNUSED_PAD src0_sel:DWORD src1_sel:BYTE_3
	v_add_u32_e32 v220, 0x2000, v178
	v_add_u32_sdwa v179, s60, v142 dst_sel:DWORD dst_unused:UNUSED_PAD src0_sel:DWORD src1_sel:BYTE_1
	ds_read_b128 v[158:161], v119
	ds_read_b128 v[166:169], v119 offset:64
	ds_read_b128 v[170:173], v119 offset:2304
	ds_read_b128 v[174:177], v119 offset:2368
	v_add_u32_e32 v162, s60, v153
	ds_read2_b64 v[182:185], v181 offset0:128 offset1:132
	ds_read2_b64 v[186:189], v218 offset0:160 offset1:164
	ds_read2_b64 v[190:193], v219 offset0:192 offset1:196
	ds_read2_b64 v[194:197], v220 offset0:128 offset1:132
	ds_read_b128 v[198:201], v119 offset:1152
	ds_read_b128 v[202:205], v119 offset:1216
	ds_read_b128 v[206:209], v119 offset:3456
	ds_read_b128 v[210:213], v119 offset:3520
	v_add_u32_e32 v178, s60, v155
	v_add_u32_sdwa v214, s60, v143 dst_sel:DWORD dst_unused:UNUSED_PAD src0_sel:DWORD src1_sel:BYTE_2
	v_add_u32_sdwa v215, s60, v143 dst_sel:DWORD dst_unused:UNUSED_PAD src0_sel:DWORD src1_sel:BYTE_3
	ds_read_b32 v136, v136 offset:41856
	ds_read_b32 v216, v162 offset:41856
	ds_read_b32 v163, v163 offset:41856
	ds_read_b32 v165, v165 offset:41856
	ds_read_b32 v217, v178 offset:41856
	ds_read_b32 v179, v179 offset:41856
	ds_read_b32 v221, v214 offset:41856
	ds_read_b32 v222, v215 offset:41856
	s_nop 0
	s_waitcnt vmcnt(7) lgkmcnt(14)
	v_mfma_f32_16x16x32_bf16 v[158:161], v[158:161], v[80:83], 0
	s_waitcnt vmcnt(6)
	v_mfma_f32_16x16x32_bf16 v[158:161], v[166:169], v[84:87], v[158:161]
	v_mfma_f32_16x16x32_bf16 v[166:169], v[170:173], v[80:83], 0
	v_mfma_f32_16x16x32_bf16 v[166:169], v[174:177], v[84:87], v[166:169]
	s_nop 0
	s_nop 6
	v_cndmask_b32_e64 v158, v166, v158, s[20:21]
	s_waitcnt lgkmcnt(7)
	v_add_f32_e32 v136, v136, v158
	v_exp_f32_e32 v162, v136
	v_cndmask_b32_e64 v136, v159, v167, s[10:11]
	v_cndmask_b32_e64 v159, v160, v168, s[12:13]
	s_waitcnt lgkmcnt(5)
	v_add_f32_e32 v159, v163, v159
	v_add_f32_e32 v136, v216, v136
	v_exp_f32_e32 v214, v159
	v_cndmask_b32_e64 v159, v161, v169, s[14:15]
	v_exp_f32_e32 v178, v136
	s_waitcnt lgkmcnt(4)
	v_add_f32_e32 v159, v165, v159
	v_exp_f32_e32 v216, v159
	v_cndmask_b32_e64 v159, v214, 0, s[12:13]
	v_cndmask_b32_e64 v158, v178, 0, s[10:11]
	v_cndmask_b32_e64 v160, 0, v178, s[10:11]
	v_cndmask_b32_e64 v161, 0, v214, s[12:13]
	v_cndmask_b32_e64 v136, 0, v162, s[20:21]
	v_cndmask_b32_e64 v166, v162, 0, s[20:21]
	v_cndmask_b32_e64 v163, v216, 0, s[14:15]
	v_cndmask_b32_e64 v165, 0, v216, s[14:15]
	v_cvt_pk_bf16_f32 v158, v136, v158
	v_cvt_pk_bf16_f32 v159, v159, v163
	v_cvt_pk_bf16_f32 v160, v166, v160
	v_cvt_pk_bf16_f32 v161, v161, v165
	s_nop 0
	v_mfma_f32_16x16x32_bf16 v[60:63], v[182:185], v[158:161], v[60:63]
	v_mfma_f32_16x16x32_bf16 v[56:59], v[186:189], v[158:161], v[56:59]
	v_mfma_f32_16x16x32_bf16 v[52:55], v[190:193], v[158:161], v[52:55]
	v_mfma_f32_16x16x32_bf16 v[48:51], v[194:197], v[158:161], v[48:51]
	s_nop 0
	ds_read2_b64 v[158:161], v181 offset0:130 offset1:134
	ds_read2_b64 v[166:169], v218 offset0:162 offset1:166
	ds_read2_b64 v[170:173], v219 offset0:194 offset1:198
	ds_read2_b64 v[174:177], v220 offset0:130 offset1:134
	ds_read_b128 v[182:185], v119 offset:3456
	ds_read_b128 v[186:189], v119 offset:3520
	ds_read_b128 v[190:193], v119 offset:5760
	ds_read_b128 v[194:197], v119 offset:5824
	v_add_u32_e32 v136, s60, v156
	v_add_u32_sdwa v165, s60, v141 dst_sel:DWORD dst_unused:UNUSED_PAD src0_sel:DWORD src1_sel:BYTE_2
	v_add_u32_sdwa v163, s60, v140 dst_sel:DWORD dst_unused:UNUSED_PAD src0_sel:DWORD src1_sel:BYTE_1
	v_add_u32_sdwa v215, s60, v141 dst_sel:DWORD dst_unused:UNUSED_PAD src0_sel:DWORD src1_sel:BYTE_3
	ds_read_b32 v136, v136 offset:41856
	ds_read_b32 v223, v163 offset:41856
	ds_read_b32 v165, v165 offset:41856
	ds_read_b32 v224, v215 offset:41856
	s_nop 0
	s_waitcnt vmcnt(5)
	v_mfma_f32_16x16x32_bf16 v[198:201], v[198:201], v[88:91], 0
	s_waitcnt vmcnt(4)
	v_mfma_f32_16x16x32_bf16 v[198:201], v[202:205], v[92:95], v[198:201]
	v_mfma_f32_16x16x32_bf16 v[202:205], v[206:209], v[88:91], 0
	v_mfma_f32_16x16x32_bf16 v[202:205], v[210:213], v[92:95], v[202:205]
	s_nop 0
	s_nop 6
	v_cndmask_b32_e64 v163, v198, v202, s[16:17]
	s_waitcnt lgkmcnt(14)
	v_add_f32_e32 v163, v217, v163
	v_cndmask_b32_e64 v198, v199, v203, s[18:19]
	v_cndmask_b32_e64 v200, v200, v204, s[6:7]
	v_exp_f32_e32 v163, v163
	v_add_f32_e32 v179, v179, v198
	s_waitcnt lgkmcnt(13)
	v_add_f32_e32 v200, v221, v200
	v_exp_f32_e32 v179, v179
	v_exp_f32_e32 v215, v200
	v_cndmask_b32_e64 v200, v201, v205, s[8:9]
	s_waitcnt lgkmcnt(12)
	v_add_f32_e32 v200, v222, v200
	v_exp_f32_e32 v217, v200
	v_cndmask_b32_e64 v198, v163, 0, s[16:17]
	v_cndmask_b32_e64 v202, 0, v163, s[16:17]
	v_pk_add_f32 v[162:163], v[162:163], 0 op_sel_hi:[1,0]
	v_cndmask_b32_e64 v199, v179, 0, s[18:19]
	v_pk_add_f32 v[162:163], v[178:179], v[162:163]
	v_cndmask_b32_e64 v200, 0, v179, s[18:19]
	v_pk_add_f32 v[162:163], v[214:215], v[162:163]
	v_cndmask_b32_e64 v201, v215, 0, s[6:7]
	v_pk_add_f32 v[162:163], v[216:217], v[162:163]
	v_cndmask_b32_e64 v203, 0, v215, s[6:7]
	v_pk_add_f32 v[130:131], v[130:131], v[162:163]
	v_cndmask_b32_e64 v204, v217, 0, s[8:9]
	v_cndmask_b32_e64 v205, 0, v217, s[8:9]
	v_cvt_pk_bf16_f32 v198, v198, v199
	v_cvt_pk_bf16_f32 v199, v201, v204
	v_cvt_pk_bf16_f32 v200, v202, v200
	v_cvt_pk_bf16_f32 v201, v203, v205
	s_nop 0
	s_waitcnt lgkmcnt(11)
	v_mfma_f32_16x16x32_bf16 v[44:47], v[158:161], v[198:201], v[44:47]
	s_waitcnt lgkmcnt(10)
	v_mfma_f32_16x16x32_bf16 v[40:43], v[166:169], v[198:201], v[40:43]
	s_waitcnt lgkmcnt(9)
	v_mfma_f32_16x16x32_bf16 v[36:39], v[170:173], v[198:201], v[36:39]
	s_waitcnt lgkmcnt(8)
	v_mfma_f32_16x16x32_bf16 v[32:35], v[174:177], v[198:201], v[32:35]
	s_nop 0
	ds_read2_b64 v[158:161], v181 offset0:134 offset1:138
	ds_read2_b64 v[166:169], v218 offset0:166 offset1:170
	ds_read2_b64 v[170:173], v219 offset0:198 offset1:202
	ds_read2_b64 v[174:177], v220 offset0:134 offset1:138
	ds_read_b128 v[198:201], v119 offset:4608
	ds_read_b128 v[202:205], v119 offset:4672
	v_add_u32_e32 v119, v148, v151
	ds_read_b128 v[206:209], v119
	ds_read_b128 v[210:213], v119 offset:64
	v_add_u32_e32 v119, s60, v154
	v_add_u32_sdwa v162, s60, v145 dst_sel:DWORD dst_unused:UNUSED_PAD src0_sel:DWORD src1_sel:BYTE_1
	v_add_u32_sdwa v163, s60, v146 dst_sel:DWORD dst_unused:UNUSED_PAD src0_sel:DWORD src1_sel:BYTE_2
	v_add_u32_sdwa v178, s60, v146 dst_sel:DWORD dst_unused:UNUSED_PAD src0_sel:DWORD src1_sel:BYTE_3
	ds_read_b32 v119, v119 offset:41856
	ds_read_b32 v179, v162 offset:41856
	ds_read_b32 v214, v163 offset:41856
	ds_read_b32 v215, v178 offset:41856
	s_nop 0
	s_waitcnt vmcnt(3) lgkmcnt(14)
	v_mfma_f32_16x16x32_bf16 v[182:185], v[182:185], v[96:99], 0
	s_waitcnt vmcnt(2)
	v_mfma_f32_16x16x32_bf16 v[182:185], v[186:189], v[100:103], v[182:185]
	v_mfma_f32_16x16x32_bf16 v[186:189], v[190:193], v[96:99], 0
	v_mfma_f32_16x16x32_bf16 v[186:189], v[194:197], v[100:103], v[186:189]
	s_nop 0
	s_nop 6
	v_cndmask_b32_e64 v162, v186, v182, s[2:3]
	v_add_f32_e32 v136, v136, v162
	v_exp_f32_e32 v162, v136
	v_cndmask_b32_e64 v136, v187, v183, s[4:5]
	v_cndmask_b32_e64 v183, v184, v188, s[22:23]
	s_waitcnt lgkmcnt(13)
	v_add_f32_e32 v165, v165, v183
	v_exp_f32_e32 v190, v165
	v_cndmask_b32_e64 v165, v185, v189, s[24:25]
	v_add_f32_e32 v136, v223, v136
	s_waitcnt lgkmcnt(12)
	v_add_f32_e32 v165, v224, v165
	v_exp_f32_e32 v178, v136
	v_exp_f32_e32 v192, v165
	v_cndmask_b32_e64 v183, v190, 0, s[22:23]
	v_cndmask_b32_e64 v185, 0, v190, s[22:23]
	v_cndmask_b32_e64 v182, 0, v178, s[4:5]
	v_cndmask_b32_e64 v184, v192, 0, s[24:25]
	v_cndmask_b32_e64 v136, 0, v162, s[2:3]
	v_cndmask_b32_e64 v163, v162, 0, s[2:3]
	v_cndmask_b32_e64 v165, v178, 0, s[4:5]
	v_cndmask_b32_e64 v186, 0, v192, s[24:25]
	v_cvt_pk_bf16_f32 v182, v136, v182
	v_cvt_pk_bf16_f32 v183, v183, v184
	v_cvt_pk_bf16_f32 v184, v163, v165
	v_cvt_pk_bf16_f32 v185, v185, v186
	s_nop 0
	s_waitcnt lgkmcnt(11)
	v_mfma_f32_16x16x32_bf16 v[28:31], v[158:161], v[182:185], v[28:31]
	s_waitcnt lgkmcnt(10)
	v_mfma_f32_16x16x32_bf16 v[24:27], v[166:169], v[182:185], v[24:27]
	s_waitcnt lgkmcnt(9)
	v_mfma_f32_16x16x32_bf16 v[20:23], v[170:173], v[182:185], v[20:23]
	s_waitcnt lgkmcnt(8)
	v_mfma_f32_16x16x32_bf16 v[16:19], v[174:177], v[182:185], v[16:19]
	s_nop 0
	ds_read2_b64 v[158:161], v220 offset0:136 offset1:140
	ds_read2_b64 v[166:169], v219 offset0:200 offset1:204
	ds_read2_b64 v[170:173], v218 offset0:168 offset1:172
	ds_read2_b64 v[174:177], v181 offset0:136 offset1:140
	s_nop 0
	s_waitcnt vmcnt(1) lgkmcnt(11)
	v_mfma_f32_16x16x32_bf16 v[182:185], v[198:201], v[104:107], 0
	s_waitcnt lgkmcnt(9)
	v_mfma_f32_16x16x32_bf16 v[186:189], v[206:209], v[104:107], 0
	s_waitcnt vmcnt(0)
	v_mfma_f32_16x16x32_bf16 v[182:185], v[202:205], v[108:111], v[182:185]
	s_waitcnt lgkmcnt(8)
	v_mfma_f32_16x16x32_bf16 v[186:189], v[210:213], v[108:111], v[186:189]
	s_nop 0
	s_nop 6
	v_cndmask_b32_e64 v136, v182, v186, s[26:27]
	s_waitcnt lgkmcnt(7)
	v_add_f32_e32 v119, v119, v136
	v_exp_f32_e32 v163, v119
	v_cndmask_b32_e64 v119, v183, v187, s[28:29]
	v_cndmask_b32_e64 v181, v184, v188, s[30:31]
	s_waitcnt lgkmcnt(6)
	v_add_f32_e32 v119, v179, v119
	s_waitcnt lgkmcnt(5)
	v_add_f32_e32 v181, v214, v181
	v_exp_f32_e32 v179, v119
	v_exp_f32_e32 v191, v181
	v_cndmask_b32_e64 v181, v185, v189, s[34:35]
	s_waitcnt lgkmcnt(4)
	v_add_f32_e32 v181, v215, v181
	v_exp_f32_e32 v193, v181
	v_cndmask_b32_e64 v119, v163, 0, s[26:27]
	v_cndmask_b32_e64 v136, 0, v163, s[26:27]
	v_pk_add_f32 v[162:163], v[162:163], 0 op_sel_hi:[1,0]
	v_cndmask_b32_e64 v183, v191, 0, s[30:31]
	v_pk_add_f32 v[162:163], v[178:179], v[162:163]
	v_cndmask_b32_e64 v185, 0, v191, s[30:31]
	v_pk_add_f32 v[162:163], v[190:191], v[162:163]
	v_cndmask_b32_e64 v184, v193, 0, s[34:35]
	v_pk_add_f32 v[162:163], v[192:193], v[162:163]
	v_cndmask_b32_e64 v165, v179, 0, s[28:29]
	v_pk_add_f32 v[124:125], v[124:125], v[162:163]
	v_cndmask_b32_e64 v181, 0, v179, s[28:29]
	v_cndmask_b32_e64 v186, 0, v193, s[34:35]
	v_cvt_pk_bf16_f32 v182, v119, v165
	v_cvt_pk_bf16_f32 v183, v183, v184
	v_cvt_pk_bf16_f32 v184, v136, v181
	v_cvt_pk_bf16_f32 v185, v185, v186
	s_nop 0
	s_waitcnt lgkmcnt(0)
	v_mfma_f32_16x16x32_bf16 v[12:15], v[174:177], v[182:185], v[12:15]
	v_mfma_f32_16x16x32_bf16 v[8:11], v[170:173], v[182:185], v[8:11]
	v_mfma_f32_16x16x32_bf16 v[4:7], v[166:169], v[182:185], v[4:7]
	v_mfma_f32_16x16x32_bf16 v[0:3], v[158:161], v[182:185], v[0:3]
	s_nop 0

.LBB0_697:
	s_add_i32 s52, s40, -2
	s_cmp_ge_u32 s52, s38
	s_cselect_b64 s[62:63], -1, 0
	s_cmp_lt_u32 s52, s39
	s_cselect_b64 s[74:75], -1, 0
	s_and_b64 s[62:63], s[62:63], s[74:75]
	s_andn2_b64 vcc, exec, s[62:63]
	s_cbranch_vccnz .LBB0_699
	v_add_u32_e32 v178, v150, v149
	v_add_u32_e32 v181, 0x6800, v178
	v_add_u32_e32 v218, 0x7000, v178
	v_add_u32_e32 v219, 0x7800, v178
	v_add_u32_e32 v178, v150, v151
	v_add_u32_e32 v119, v148, v149
	v_add_u32_e32 v136, s60, v152
	v_add_u32_sdwa v163, s60, v144 dst_sel:DWORD dst_unused:UNUSED_PAD src0_sel:DWORD src1_sel:BYTE_2
	v_add_u32_sdwa v165, s60, v144 dst_sel:DWORD dst_unused:UNUSED_PAD src0_sel:DWORD src1_sel:BYTE_3
	v_add_u32_e32 v220, 0x6800, v178
	v_add_u32_sdwa v179, s60, v142 dst_sel:DWORD dst_unused:UNUSED_PAD src0_sel:DWORD src1_sel:BYTE_1
	ds_read_b128 v[158:161], v119 offset:18432
	ds_read_b128 v[166:169], v119 offset:18496
	ds_read_b128 v[170:173], v119 offset:20736
	ds_read_b128 v[174:177], v119 offset:20800
	v_add_u32_e32 v162, s60, v153
	ds_read2_b64 v[182:185], v181 offset0:128 offset1:132
	ds_read2_b64 v[186:189], v218 offset0:160 offset1:164
	ds_read2_b64 v[190:193], v219 offset0:192 offset1:196
	ds_read2_b64 v[194:197], v220 offset0:128 offset1:132
	ds_read_b128 v[198:201], v119 offset:19584
	ds_read_b128 v[202:205], v119 offset:19648
	ds_read_b128 v[206:209], v119 offset:21888
	ds_read_b128 v[210:213], v119 offset:21952
	v_add_u32_e32 v178, s60, v155
	v_add_u32_sdwa v214, s60, v143 dst_sel:DWORD dst_unused:UNUSED_PAD src0_sel:DWORD src1_sel:BYTE_2
	v_add_u32_sdwa v215, s60, v143 dst_sel:DWORD dst_unused:UNUSED_PAD src0_sel:DWORD src1_sel:BYTE_3
	ds_read_b32 v136, v136 offset:41984
	ds_read_b32 v216, v162 offset:41984
	ds_read_b32 v163, v163 offset:41984
	ds_read_b32 v165, v165 offset:41984
	ds_read_b32 v217, v178 offset:41984
	ds_read_b32 v179, v179 offset:41984
	ds_read_b32 v221, v214 offset:41984
	ds_read_b32 v222, v215 offset:41984
	s_nop 0
	s_waitcnt vmcnt(7) lgkmcnt(14)
	v_mfma_f32_16x16x32_bf16 v[158:161], v[158:161], v[80:83], 0
	s_waitcnt vmcnt(6)
	v_mfma_f32_16x16x32_bf16 v[158:161], v[166:169], v[84:87], v[158:161]
	v_mfma_f32_16x16x32_bf16 v[166:169], v[170:173], v[80:83], 0
	v_mfma_f32_16x16x32_bf16 v[166:169], v[174:177], v[84:87], v[166:169]
	s_nop 0
	s_nop 6
	v_cndmask_b32_e64 v158, v166, v158, s[20:21]
	s_waitcnt lgkmcnt(7)
	v_add_f32_e32 v136, v136, v158
	v_exp_f32_e32 v162, v136
	v_cndmask_b32_e64 v136, v159, v167, s[10:11]
	v_cndmask_b32_e64 v159, v160, v168, s[12:13]
	s_waitcnt lgkmcnt(5)
	v_add_f32_e32 v159, v163, v159
	v_add_f32_e32 v136, v216, v136
	v_exp_f32_e32 v214, v159
	v_cndmask_b32_e64 v159, v161, v169, s[14:15]
	v_exp_f32_e32 v178, v136
	s_waitcnt lgkmcnt(4)
	v_add_f32_e32 v159, v165, v159
	v_exp_f32_e32 v216, v159
	v_cndmask_b32_e64 v159, v214, 0, s[12:13]
	v_cndmask_b32_e64 v158, v178, 0, s[10:11]
	v_cndmask_b32_e64 v160, 0, v178, s[10:11]
	v_cndmask_b32_e64 v161, 0, v214, s[12:13]
	v_cndmask_b32_e64 v136, 0, v162, s[20:21]
	v_cndmask_b32_e64 v166, v162, 0, s[20:21]
	v_cndmask_b32_e64 v163, v216, 0, s[14:15]
	v_cndmask_b32_e64 v165, 0, v216, s[14:15]
	v_cvt_pk_bf16_f32 v158, v136, v158
	v_cvt_pk_bf16_f32 v159, v159, v163
	v_cvt_pk_bf16_f32 v160, v166, v160
	v_cvt_pk_bf16_f32 v161, v161, v165
	s_nop 0
	v_mfma_f32_16x16x32_bf16 v[60:63], v[182:185], v[158:161], v[60:63]
	v_mfma_f32_16x16x32_bf16 v[56:59], v[186:189], v[158:161], v[56:59]
	v_mfma_f32_16x16x32_bf16 v[52:55], v[190:193], v[158:161], v[52:55]
	v_mfma_f32_16x16x32_bf16 v[48:51], v[194:197], v[158:161], v[48:51]
	s_nop 0
	ds_read2_b64 v[158:161], v181 offset0:130 offset1:134
	ds_read2_b64 v[166:169], v218 offset0:162 offset1:166
	ds_read2_b64 v[170:173], v219 offset0:194 offset1:198
	ds_read2_b64 v[174:177], v220 offset0:130 offset1:134
	ds_read_b128 v[182:185], v119 offset:21888
	ds_read_b128 v[186:189], v119 offset:21952
	ds_read_b128 v[190:193], v119 offset:24192
	ds_read_b128 v[194:197], v119 offset:24256
	v_add_u32_e32 v136, s60, v156
	v_add_u32_sdwa v165, s60, v141 dst_sel:DWORD dst_unused:UNUSED_PAD src0_sel:DWORD src1_sel:BYTE_2
	v_add_u32_sdwa v163, s60, v140 dst_sel:DWORD dst_unused:UNUSED_PAD src0_sel:DWORD src1_sel:BYTE_1
	v_add_u32_sdwa v215, s60, v141 dst_sel:DWORD dst_unused:UNUSED_PAD src0_sel:DWORD src1_sel:BYTE_3
	ds_read_b32 v136, v136 offset:41984
	ds_read_b32 v223, v163 offset:41984
	ds_read_b32 v165, v165 offset:41984
	ds_read_b32 v224, v215 offset:41984
	s_nop 0
	s_waitcnt vmcnt(5)
	v_mfma_f32_16x16x32_bf16 v[198:201], v[198:201], v[88:91], 0
	s_waitcnt vmcnt(4)
	v_mfma_f32_16x16x32_bf16 v[198:201], v[202:205], v[92:95], v[198:201]
	v_mfma_f32_16x16x32_bf16 v[202:205], v[206:209], v[88:91], 0
	v_mfma_f32_16x16x32_bf16 v[202:205], v[210:213], v[92:95], v[202:205]
	s_nop 0
	s_nop 6
	v_cndmask_b32_e64 v163, v198, v202, s[16:17]
	s_waitcnt lgkmcnt(14)
	v_add_f32_e32 v163, v217, v163
	v_cndmask_b32_e64 v198, v199, v203, s[18:19]
	v_cndmask_b32_e64 v200, v200, v204, s[6:7]
	v_exp_f32_e32 v163, v163
	v_add_f32_e32 v179, v179, v198
	s_waitcnt lgkmcnt(13)
	v_add_f32_e32 v200, v221, v200
	v_exp_f32_e32 v179, v179
	v_exp_f32_e32 v215, v200
	v_cndmask_b32_e64 v200, v201, v205, s[8:9]
	s_waitcnt lgkmcnt(12)
	v_add_f32_e32 v200, v222, v200
	v_exp_f32_e32 v217, v200
	v_cndmask_b32_e64 v198, v163, 0, s[16:17]
	v_cndmask_b32_e64 v202, 0, v163, s[16:17]
	v_pk_add_f32 v[162:163], v[162:163], 0 op_sel_hi:[1,0]
	v_cndmask_b32_e64 v199, v179, 0, s[18:19]
	v_pk_add_f32 v[162:163], v[178:179], v[162:163]
	v_cndmask_b32_e64 v200, 0, v179, s[18:19]
	v_pk_add_f32 v[162:163], v[214:215], v[162:163]
	v_cndmask_b32_e64 v201, v215, 0, s[6:7]
	v_pk_add_f32 v[162:163], v[216:217], v[162:163]
	v_cndmask_b32_e64 v203, 0, v215, s[6:7]
	v_pk_add_f32 v[130:131], v[130:131], v[162:163]
	v_cndmask_b32_e64 v204, v217, 0, s[8:9]
	v_cndmask_b32_e64 v205, 0, v217, s[8:9]
	v_cvt_pk_bf16_f32 v198, v198, v199
	v_cvt_pk_bf16_f32 v199, v201, v204
	v_cvt_pk_bf16_f32 v200, v202, v200
	v_cvt_pk_bf16_f32 v201, v203, v205
	s_nop 0
	s_waitcnt lgkmcnt(11)
	v_mfma_f32_16x16x32_bf16 v[44:47], v[158:161], v[198:201], v[44:47]
	s_waitcnt lgkmcnt(10)
	v_mfma_f32_16x16x32_bf16 v[40:43], v[166:169], v[198:201], v[40:43]
	s_waitcnt lgkmcnt(9)
	v_mfma_f32_16x16x32_bf16 v[36:39], v[170:173], v[198:201], v[36:39]
	s_waitcnt lgkmcnt(8)
	v_mfma_f32_16x16x32_bf16 v[32:35], v[174:177], v[198:201], v[32:35]
	s_nop 0
	ds_read2_b64 v[158:161], v181 offset0:134 offset1:138
	ds_read2_b64 v[166:169], v218 offset0:166 offset1:170
	ds_read2_b64 v[170:173], v219 offset0:198 offset1:202
	ds_read2_b64 v[174:177], v220 offset0:134 offset1:138
	ds_read_b128 v[198:201], v119 offset:23040
	ds_read_b128 v[202:205], v119 offset:23104
	v_add_u32_e32 v119, v148, v151
	ds_read_b128 v[206:209], v119 offset:18432
	ds_read_b128 v[210:213], v119 offset:18496
	v_add_u32_e32 v119, s60, v154
	v_add_u32_sdwa v162, s60, v145 dst_sel:DWORD dst_unused:UNUSED_PAD src0_sel:DWORD src1_sel:BYTE_1
	v_add_u32_sdwa v163, s60, v146 dst_sel:DWORD dst_unused:UNUSED_PAD src0_sel:DWORD src1_sel:BYTE_2
	v_add_u32_sdwa v178, s60, v146 dst_sel:DWORD dst_unused:UNUSED_PAD src0_sel:DWORD src1_sel:BYTE_3
	ds_read_b32 v119, v119 offset:41984
	ds_read_b32 v179, v162 offset:41984
	ds_read_b32 v214, v163 offset:41984
	ds_read_b32 v215, v178 offset:41984
	s_nop 0
	s_waitcnt vmcnt(3) lgkmcnt(14)
	v_mfma_f32_16x16x32_bf16 v[182:185], v[182:185], v[96:99], 0
	s_waitcnt vmcnt(2)
	v_mfma_f32_16x16x32_bf16 v[182:185], v[186:189], v[100:103], v[182:185]
	v_mfma_f32_16x16x32_bf16 v[186:189], v[190:193], v[96:99], 0
	v_mfma_f32_16x16x32_bf16 v[186:189], v[194:197], v[100:103], v[186:189]
	s_nop 0
	s_nop 6
	v_cndmask_b32_e64 v162, v186, v182, s[2:3]
	v_add_f32_e32 v136, v136, v162
	v_exp_f32_e32 v162, v136
	v_cndmask_b32_e64 v136, v187, v183, s[4:5]
	v_cndmask_b32_e64 v183, v184, v188, s[22:23]
	s_waitcnt lgkmcnt(13)
	v_add_f32_e32 v165, v165, v183
	v_exp_f32_e32 v190, v165
	v_cndmask_b32_e64 v165, v185, v189, s[24:25]
	v_add_f32_e32 v136, v223, v136
	s_waitcnt lgkmcnt(12)
	v_add_f32_e32 v165, v224, v165
	v_exp_f32_e32 v178, v136
	v_exp_f32_e32 v192, v165
	v_cndmask_b32_e64 v183, v190, 0, s[22:23]
	v_cndmask_b32_e64 v185, 0, v190, s[22:23]
	v_cndmask_b32_e64 v182, 0, v178, s[4:5]
	v_cndmask_b32_e64 v184, v192, 0, s[24:25]
	v_cndmask_b32_e64 v136, 0, v162, s[2:3]
	v_cndmask_b32_e64 v163, v162, 0, s[2:3]
	v_cndmask_b32_e64 v165, v178, 0, s[4:5]
	v_cndmask_b32_e64 v186, 0, v192, s[24:25]
	v_cvt_pk_bf16_f32 v182, v136, v182
	v_cvt_pk_bf16_f32 v183, v183, v184
	v_cvt_pk_bf16_f32 v184, v163, v165
	v_cvt_pk_bf16_f32 v185, v185, v186
	s_nop 0
	s_waitcnt lgkmcnt(11)
	v_mfma_f32_16x16x32_bf16 v[28:31], v[158:161], v[182:185], v[28:31]
	s_waitcnt lgkmcnt(10)
	v_mfma_f32_16x16x32_bf16 v[24:27], v[166:169], v[182:185], v[24:27]
	s_waitcnt lgkmcnt(9)
	v_mfma_f32_16x16x32_bf16 v[20:23], v[170:173], v[182:185], v[20:23]
	s_waitcnt lgkmcnt(8)
	v_mfma_f32_16x16x32_bf16 v[16:19], v[174:177], v[182:185], v[16:19]
	s_nop 0
	ds_read2_b64 v[158:161], v220 offset0:136 offset1:140
	ds_read2_b64 v[166:169], v219 offset0:200 offset1:204
	ds_read2_b64 v[170:173], v218 offset0:168 offset1:172
	ds_read2_b64 v[174:177], v181 offset0:136 offset1:140
	s_nop 0
	s_waitcnt vmcnt(1) lgkmcnt(11)
	v_mfma_f32_16x16x32_bf16 v[182:185], v[198:201], v[104:107], 0
	s_waitcnt lgkmcnt(9)
	v_mfma_f32_16x16x32_bf16 v[186:189], v[206:209], v[104:107], 0
	s_waitcnt vmcnt(0)
	v_mfma_f32_16x16x32_bf16 v[182:185], v[202:205], v[108:111], v[182:185]
	s_waitcnt lgkmcnt(8)
	v_mfma_f32_16x16x32_bf16 v[186:189], v[210:213], v[108:111], v[186:189]
	s_nop 0
	s_nop 6
	v_cndmask_b32_e64 v136, v182, v186, s[26:27]
	s_waitcnt lgkmcnt(7)
	v_add_f32_e32 v119, v119, v136
	v_exp_f32_e32 v163, v119
	v_cndmask_b32_e64 v119, v183, v187, s[28:29]
	v_cndmask_b32_e64 v181, v184, v188, s[30:31]
	s_waitcnt lgkmcnt(6)
	v_add_f32_e32 v119, v179, v119
	s_waitcnt lgkmcnt(5)
	v_add_f32_e32 v181, v214, v181
	v_exp_f32_e32 v179, v119
	v_exp_f32_e32 v191, v181
	v_cndmask_b32_e64 v181, v185, v189, s[34:35]
	s_waitcnt lgkmcnt(4)
	v_add_f32_e32 v181, v215, v181
	v_exp_f32_e32 v193, v181
	v_cndmask_b32_e64 v119, v163, 0, s[26:27]
	v_cndmask_b32_e64 v136, 0, v163, s[26:27]
	v_pk_add_f32 v[162:163], v[162:163], 0 op_sel_hi:[1,0]
	v_cndmask_b32_e64 v183, v191, 0, s[30:31]
	v_pk_add_f32 v[162:163], v[178:179], v[162:163]
	v_cndmask_b32_e64 v185, 0, v191, s[30:31]
	v_pk_add_f32 v[162:163], v[190:191], v[162:163]
	v_cndmask_b32_e64 v184, v193, 0, s[34:35]
	v_pk_add_f32 v[162:163], v[192:193], v[162:163]
	v_cndmask_b32_e64 v165, v179, 0, s[28:29]
	v_pk_add_f32 v[124:125], v[124:125], v[162:163]
	v_cndmask_b32_e64 v181, 0, v179, s[28:29]
	v_cndmask_b32_e64 v186, 0, v193, s[34:35]
	v_cvt_pk_bf16_f32 v182, v119, v165
	v_cvt_pk_bf16_f32 v183, v183, v184
	v_cvt_pk_bf16_f32 v184, v136, v181
	v_cvt_pk_bf16_f32 v185, v185, v186
	s_nop 0
	s_waitcnt lgkmcnt(0)
	v_mfma_f32_16x16x32_bf16 v[12:15], v[174:177], v[182:185], v[12:15]
	v_mfma_f32_16x16x32_bf16 v[8:11], v[170:173], v[182:185], v[8:11]
	v_mfma_f32_16x16x32_bf16 v[4:7], v[166:169], v[182:185], v[4:7]
	v_mfma_f32_16x16x32_bf16 v[0:3], v[158:161], v[182:185], v[0:3]
	s_nop 0
